# plus: critical-path cross-quad reductions in attention via v_permlane16/32_swap and DPP instead of ds_bpermute
# baseline (speedup 1.0000x reference)
.LBB0_182:
	s_barrier
	global_load_dwordx4 v[48:51], v[92:93], off offset:48
	global_load_dwordx4 v[52:55], v[92:93], off offset:32
	global_load_dwordx4 v[56:59], v[92:93], off offset:16
	global_load_dwordx4 v[60:63], v[92:93], off
	s_waitcnt vmcnt(12)
	v_and_b32_e32 v159, 0xffff0000, v4
	v_lshlrev_b32_e32 v158, 16, v4
	v_and_b32_e32 v151, 0xffff0000, v5
	v_lshlrev_b32_e32 v150, 16, v5
	v_pk_mul_f32 v[162:163], v[158:159], v[158:159]
	v_pk_mul_f32 v[154:155], v[150:151], v[150:151]
	v_add_f32_e32 v108, v162, v163
	v_and_b32_e32 v145, 0xffff0000, v6
	v_lshlrev_b32_e32 v144, 16, v6
	v_add_f32_e32 v108, v154, v108
	v_pk_mul_f32 v[106:107], v[144:145], v[144:145]
	v_add_f32_e32 v108, v155, v108
	v_and_b32_e32 v101, 0xffff0000, v7
	v_lshlrev_b32_e32 v100, 16, v7
	v_add_f32_e32 v106, v106, v108
	v_pk_mul_f32 v[102:103], v[100:101], v[100:101]
	v_add_f32_e32 v106, v107, v106
	s_waitcnt vmcnt(8)
	v_and_b32_e32 v161, 0xffff0000, v12
	v_lshlrev_b32_e32 v160, 16, v12
	v_add_f32_e32 v102, v102, v106
	v_pk_mul_f32 v[164:165], v[160:161], v[160:161]
	v_add_f32_e32 v102, v103, v102
	v_and_b32_e32 v153, 0xffff0000, v13
	v_lshlrev_b32_e32 v152, 16, v13
	v_add_f32_e32 v102, v164, v102
	v_pk_mul_f32 v[156:157], v[152:153], v[152:153]
	v_add_f32_e32 v102, v165, v102
	v_and_b32_e32 v147, 0xffff0000, v14
	v_lshlrev_b32_e32 v146, 16, v14
	v_add_f32_e32 v102, v156, v102
	v_pk_mul_f32 v[148:149], v[146:147], v[146:147]
	v_add_f32_e32 v102, v157, v102
	v_and_b32_e32 v143, 0xffff0000, v15
	v_lshlrev_b32_e32 v142, 16, v15
	v_add_f32_e32 v102, v148, v102
	v_pk_mul_f32 v[104:105], v[142:143], v[142:143]
	v_add_f32_e32 v102, v149, v102
	v_add_f32_e32 v102, v104, v102
	v_lshlrev_b32_e32 v140, 16, v8
	v_add_f32_e32 v102, v105, v102
	v_and_b32_e32 v139, 0xffff0000, v8
	v_fmac_f32_e32 v102, v140, v140
	v_lshlrev_b32_e32 v138, 16, v9
	v_fmac_f32_e32 v102, v139, v139
	v_and_b32_e32 v137, 0xffff0000, v9
	v_fmac_f32_e32 v102, v138, v138
	v_lshlrev_b32_e32 v136, 16, v10
	v_fmac_f32_e32 v102, v137, v137
	v_and_b32_e32 v135, 0xffff0000, v10
	v_fmac_f32_e32 v102, v136, v136
	v_lshlrev_b32_e32 v134, 16, v11
	v_fmac_f32_e32 v102, v135, v135
	v_and_b32_e32 v99, 0xffff0000, v11
	v_and_b32_e32 v64, 0xffff0000, v16
	v_lshlrev_b32_e32 v65, 16, v16
	v_fmac_f32_e32 v102, v134, v134
	v_pk_mul_f32 v[72:73], v[64:65], v[64:65]
	v_fmac_f32_e32 v102, v99, v99
	v_and_b32_e32 v68, 0xffff0000, v17
	v_lshlrev_b32_e32 v69, 16, v17
	v_add_f32_e32 v73, v73, v102
	v_pk_mul_f32 v[74:75], v[68:69], v[68:69]
	v_add_f32_e32 v72, v72, v73
	v_and_b32_e32 v70, 0xffff0000, v18
	v_lshlrev_b32_e32 v71, 16, v18
	v_add_f32_e32 v72, v75, v72
	v_pk_mul_f32 v[76:77], v[70:71], v[70:71]
	v_add_f32_e32 v72, v74, v72
	v_and_b32_e32 v66, 0xffff0000, v19
	v_lshlrev_b32_e32 v67, 16, v19
	v_add_f32_e32 v72, v77, v72
	v_pk_mul_f32 v[78:79], v[66:67], v[66:67]
	v_add_f32_e32 v72, v76, v72
	v_add_f32_e32 v72, v79, v72
	v_add_f32_e32 v72, v78, v72
	s_nop 1
	s_waitcnt lgkmcnt(0)
	v_add_f32_dpp v72, v72, v72 quad_perm:[1,0,3,2] row_mask:0xf bank_mask:0xf
	v_fmamk_f32 v72, v72, 0x3c800000, v180
	v_rsq_f32_e32 v108, v72
	s_nop 0
	v_pk_mul_f32 v[72:73], v[108:109], v[158:159] op_sel_hi:[0,1]
	s_waitcnt vmcnt(0)
	v_pk_mul_f32 v[106:107], v[60:61], v[72:73]
	v_pk_mul_f32 v[60:61], v[108:109], v[150:151] op_sel_hi:[0,1]
	v_pk_mul_f32 v[104:105], v[62:63], v[60:61]
	v_pk_mul_f32 v[60:61], v[108:109], v[144:145] op_sel_hi:[0,1]
	v_pk_mul_f32 v[102:103], v[56:57], v[60:61]
	v_pk_mul_f32 v[56:57], v[108:109], v[100:101] op_sel_hi:[0,1]
	v_pk_mul_f32 v[100:101], v[58:59], v[56:57]
	v_pk_mul_f32 v[56:57], v[108:109], v[160:161] op_sel_hi:[0,1]
	v_pk_mul_f32 v[78:79], v[52:53], v[56:57]
	v_pk_mul_f32 v[52:53], v[108:109], v[152:153] op_sel_hi:[0,1]
	v_pk_mul_f32 v[76:77], v[54:55], v[52:53]
	v_pk_mul_f32 v[52:53], v[108:109], v[146:147] op_sel_hi:[0,1]
	v_pk_mul_f32 v[74:75], v[48:49], v[52:53]
	v_pk_mul_f32 v[48:49], v[108:109], v[142:143] op_sel_hi:[0,1]
	v_pk_mul_f32 v[72:73], v[50:51], v[48:49]
	global_load_dwordx4 v[48:51], v[92:93], off offset:112
	global_load_dwordx4 v[52:55], v[92:93], off offset:96
	global_load_dwordx4 v[56:59], v[92:93], off offset:80
	global_load_dwordx4 v[60:63], v[92:93], off offset:64
	s_and_saveexec_b64 s[88:89], s[84:85]
	s_cbranch_execz .LBB0_184
	global_load_dwordx4 v[142:145], v[84:85], off offset:48
	global_load_dwordx4 v[146:149], v[84:85], off offset:32
	global_load_dwordx4 v[150:153], v[84:85], off offset:16
	global_load_dwordx4 v[154:157], v[84:85], off
	s_waitcnt vmcnt(2)
	v_pk_mul_f32 v[158:159], v[106:107], v[146:147]
	v_pk_mul_f32 v[146:147], v[78:79], v[146:147]
	s_waitcnt vmcnt(0)
	v_pk_fma_f32 v[78:79], v[78:79], v[154:155], v[158:159]
	v_pk_fma_f32 v[106:107], v[106:107], v[154:155], v[146:147] neg_lo:[0,0,1] neg_hi:[0,0,1]
	v_pk_mul_f32 v[146:147], v[104:105], v[148:149]
	v_pk_mul_f32 v[148:149], v[76:77], v[148:149]
	v_pk_fma_f32 v[76:77], v[76:77], v[156:157], v[146:147]
	v_pk_mul_f32 v[146:147], v[102:103], v[142:143]
	v_pk_mul_f32 v[142:143], v[74:75], v[142:143]
	v_pk_fma_f32 v[104:105], v[104:105], v[156:157], v[148:149] neg_lo:[0,0,1] neg_hi:[0,0,1]
	v_pk_fma_f32 v[102:103], v[102:103], v[150:151], v[142:143] neg_lo:[0,0,1] neg_hi:[0,0,1]
	v_pk_mul_f32 v[142:143], v[100:101], v[144:145]
	v_pk_mul_f32 v[144:145], v[72:73], v[144:145]
	v_pk_fma_f32 v[74:75], v[74:75], v[150:151], v[146:147]
	v_pk_fma_f32 v[100:101], v[100:101], v[152:153], v[144:145] neg_lo:[0,0,1] neg_hi:[0,0,1]
	v_pk_fma_f32 v[72:73], v[72:73], v[152:153], v[142:143]

.LBB0_189:
	v_readlane_b32 s4, v244, 10
	s_xor_b64 s[2:3], s[2:3], -1
	s_lshl_b64 s[94:95], s[90:91], 2
	v_readlane_b32 s16, v244, 22
	v_readlane_b32 s17, v244, 23
	s_add_u32 s94, s16, s94
	s_addc_u32 s95, s17, s95
	ds_read_b128 v[134:137], v117
	ds_read_b128 v[138:141], v117 offset:64
	global_load_dword v99, v3, s[94:95]
	ds_read_b128 v[142:145], v118
	ds_read_b128 v[146:149], v118 offset:64
	s_waitcnt lgkmcnt(3)
	v_mfma_f32_16x16x32_bf16 v[134:137], v[134:137], v[72:75], 0
	v_readlane_b32 s6, v244, 12
	v_readlane_b32 s7, v244, 13
	s_mov_b32 s4, 0xf149f2ca
	s_waitcnt lgkmcnt(1)
	v_mfma_f32_16x16x32_bf16 v[142:145], v[142:145], v[72:75], 0
	v_readlane_b32 s6, v243, 12
	v_mov_b32_e32 v100, s4
	v_readlane_b32 s7, v243, 13
	v_mfma_f32_16x16x32_bf16 v[134:137], v[138:141], v[68:71], v[134:137]
	ds_read_b128 v[138:141], v119
	v_mov_b32_e32 v178, s4
	v_mov_b32_e32 v216, s4
	s_waitcnt lgkmcnt(1)
	v_mfma_f32_16x16x32_bf16 v[142:145], v[146:149], v[68:71], v[142:145]
	ds_read_b128 v[146:149], v119 offset:64
	ds_read_b128 v[150:153], v120
	ds_read_b128 v[154:157], v120 offset:64
	ds_read_b128 v[158:161], v121
	ds_read_b128 v[162:165], v121 offset:64
	v_cndmask_b32_e64 v100, v100, v134, s[6:7]
	s_waitcnt lgkmcnt(5)
	v_mfma_f32_16x16x32_bf16 v[138:141], v[138:141], v[72:75], 0
	v_readlane_b32 s6, v243, 14
	v_readlane_b32 s7, v243, 15
	v_mov_b32_e32 v218, s4
	s_waitcnt lgkmcnt(1)
	v_mfma_f32_16x16x32_bf16 v[158:161], v[158:161], v[72:75], 0
	v_mov_b32_e32 v220, s4
	v_mov_b32_e32 v222, s4
	v_readlane_b32 s5, v244, 11
	v_mfma_f32_16x16x32_bf16 v[138:141], v[146:149], v[68:71], v[138:141]
	ds_read_b128 v[146:149], v122
	ds_read_b128 v[166:169], v122 offset:64
	ds_read_b128 v[170:173], v123
	ds_read_b128 v[174:177], v123 offset:64
	ds_read_b128 v[196:199], v124
	ds_read_b128 v[200:203], v124 offset:64
	ds_read_b128 v[204:207], v125
	ds_read_b128 v[208:211], v125 offset:64
	v_readlane_b32 s8, v244, 14
	s_waitcnt lgkmcnt(8)
	v_mfma_f32_16x16x32_bf16 v[158:161], v[162:165], v[68:71], v[158:161]
	v_cndmask_b32_e64 v163, v184, v135, s[6:7]
	v_readlane_b32 s6, v243, 16
	v_readlane_b32 s7, v243, 17
	s_waitcnt lgkmcnt(7)
	v_mfma_f32_16x16x32_bf16 v[146:149], v[146:149], v[72:75], 0
	v_mov_b32_e32 v162, s4
	v_cndmask_b32_e64 v165, v184, v136, s[6:7]
	v_readlane_b32 s6, v243, 18
	v_readlane_b32 s7, v243, 19
	s_waitcnt lgkmcnt(6)
	v_mfma_f32_16x16x32_bf16 v[146:149], v[166:169], v[68:71], v[146:149]
	v_cndmask_b32_e64 v158, v162, v158, s[36:37]
	v_cndmask_b32_e64 v166, v184, v137, s[6:7]
	v_readlane_b32 s6, v243, 20
	v_readlane_b32 s7, v243, 21
	v_mfma_f32_16x16x32_bf16 v[150:153], v[150:153], v[72:75], 0
	v_cndmask_b32_e64 v159, v184, v159, s[38:39]
	v_cndmask_b32_e64 v167, v178, v142, s[6:7]
	v_readlane_b32 s6, v243, 22
	v_readlane_b32 s7, v243, 23
	v_mfma_f32_16x16x32_bf16 v[150:153], v[154:157], v[68:71], v[150:153]
	ds_read_b128 v[154:157], v126
	ds_read_b128 v[212:215], v126 offset:64
	v_cndmask_b32_e64 v168, v184, v143, s[6:7]
	v_readlane_b32 s6, v243, 24
	v_readlane_b32 s7, v243, 25
	s_waitcnt lgkmcnt(7)
	v_mfma_f32_16x16x32_bf16 v[134:137], v[170:173], v[72:75], 0
	v_cndmask_b32_e64 v171, v216, v138, s[0:1]
	v_cndmask_b32_e64 v169, v184, v144, s[6:7]
	v_readlane_b32 s6, v243, 26
	v_readlane_b32 s7, v243, 27
	s_waitcnt lgkmcnt(6)
	v_mfma_f32_16x16x32_bf16 v[134:137], v[174:177], v[68:71], v[134:137]
	v_cndmask_b32_e64 v172, v184, v139, s[20:21]
	v_cndmask_b32_e64 v170, v184, v145, s[6:7]
	v_cndmask_b32_e64 v173, v184, v140, s[22:23]
	s_waitcnt lgkmcnt(5)
	v_mfma_f32_16x16x32_bf16 v[142:145], v[196:199], v[72:75], 0
	v_cndmask_b32_e64 v174, v184, v141, s[24:25]
	v_cndmask_b32_e64 v150, v218, v150, s[26:27]
	v_cndmask_b32_e64 v151, v184, v151, s[28:29]
	s_waitcnt lgkmcnt(4)
	v_mfma_f32_16x16x32_bf16 v[138:141], v[200:203], v[68:71], v[142:145]
	v_cndmask_b32_e64 v152, v184, v152, s[30:31]
	v_cndmask_b32_e64 v153, v184, v153, s[34:35]
	v_mov_b32_e32 v164, s4
	s_waitcnt lgkmcnt(3)
	v_mfma_f32_16x16x32_bf16 v[142:145], v[204:207], v[72:75], 0
	v_cndmask_b32_e64 v160, v184, v160, s[40:41]
	v_cndmask_b32_e64 v161, v184, v161, s[42:43]
	v_cndmask_b32_e64 v146, v164, v146, s[44:45]
	s_waitcnt lgkmcnt(1)
	v_mfma_f32_16x16x32_bf16 v[72:75], v[154:157], v[72:75], 0
	v_cndmask_b32_e64 v147, v184, v147, s[46:47]
	v_cndmask_b32_e64 v148, v184, v148, s[48:49]
	v_cndmask_b32_e64 v149, v184, v149, s[50:51]
	v_mfma_f32_16x16x32_bf16 v[142:145], v[208:211], v[68:71], v[142:145]
	v_cndmask_b32_e64 v134, v220, v134, s[52:53]
	v_cndmask_b32_e64 v135, v184, v135, s[54:55]
	v_readlane_b32 s9, v244, 15
	s_waitcnt lgkmcnt(0)
	v_mfma_f32_16x16x32_bf16 v[68:71], v[212:215], v[68:71], v[72:75]
	v_readlane_b32 s10, v244, 16
	s_nop 1
	v_cndmask_b32_e64 v154, v184, v143, s[70:71]
	v_cndmask_b32_e64 v155, v184, v144, s[72:73]
	s_waitcnt vmcnt(0)
	v_mul_f32_e32 v72, 0x3fb8aa3b, v99
	v_max3_f32 v72, v72, v100, v163
	v_max3_f32 v72, v72, v165, v166
	v_max3_f32 v72, v72, v167, v168
	v_max3_f32 v72, v72, v169, v170
	v_max3_f32 v72, v72, v171, v172
	v_max3_f32 v72, v72, v173, v174
	v_max3_f32 v72, v72, v150, v151
	v_max3_f32 v72, v72, v152, v153
	v_max3_f32 v72, v72, v158, v159
	v_max3_f32 v72, v72, v160, v161
	v_max3_f32 v72, v72, v146, v147
	v_max3_f32 v72, v72, v148, v149
	v_cndmask_b32_e64 v73, v184, v136, s[56:57]
	v_cndmask_b32_e64 v74, v184, v137, s[58:59]
	v_max3_f32 v72, v72, v134, v135
	v_cndmask_b32_e64 v75, v222, v138, s[60:61]
	v_cndmask_b32_e64 v136, v184, v139, s[62:63]
	v_max3_f32 v72, v72, v73, v74
	v_max3_f32 v72, v72, v75, v136
	v_cndmask_b32_e64 v137, v184, v140, s[64:65]
	v_cndmask_b32_e64 v138, v184, v141, s[66:67]
	v_max3_f32 v139, v72, v137, v138
	v_mov_b32_e32 v72, s4
	v_cndmask_b32_e64 v140, v72, v142, s[68:69]
	v_max3_f32 v72, v139, v140, v154
	v_cndmask_b32_e64 v162, v184, v145, s[74:75]
	v_max3_f32 v139, v72, v155, v162
	v_mov_b32_e32 v72, s4
	v_cndmask_b32_e64 v164, v72, v68, s[76:77]
	v_cndmask_b32_e64 v175, v184, v69, s[78:79]
	v_max3_f32 v68, v139, v164, v175
	v_cndmask_b32_e64 v176, v184, v70, s[80:81]
	v_cndmask_b32_e64 v177, v184, v71, s[82:83]
	v_max3_f32 v68, v68, v176, v177
	v_mov_b32_e32 v69, v68
	s_nop 1
	v_permlane16_swap_b32 v69, v68
	s_mov_b32 s4, 0x3fb8aa3b
	v_readlane_b32 s11, v244, 17
	v_readlane_b32 s12, v244, 18
	v_readlane_b32 s13, v244, 19
	s_waitcnt lgkmcnt(0)
	v_max_f32_e32 v69, v69, v69
	v_max_f32_e32 v68, v68, v69
	v_mov_b32_e32 v69, v68
	s_nop 1
	v_permlane32_swap_b32 v69, v68
	v_readlane_b32 s14, v244, 20
	v_readlane_b32 s15, v244, 21
	v_readlane_b32 s18, v244, 24
	v_readlane_b32 s19, v244, 25
	s_waitcnt lgkmcnt(0)
	v_max_f32_e32 v69, v69, v69
	v_max_f32_e32 v178, v68, v69
	v_sub_f32_e32 v68, v100, v178
	v_exp_f32_e32 v72, v68
	v_sub_f32_e32 v68, v163, v178
	v_exp_f32_e32 v100, v68
	v_sub_f32_e32 v69, v165, v178
	v_exp_f32_e32 v139, v69
	v_sub_f32_e32 v69, v166, v178
	v_exp_f32_e32 v141, v69
	v_sub_f32_e32 v69, v167, v178
	v_add_f32_e32 v68, 0, v72
	v_exp_f32_e32 v142, v69
	v_sub_f32_e32 v69, v168, v178
	v_add_f32_e32 v68, v100, v68
	v_exp_f32_e32 v143, v69
	v_sub_f32_e32 v69, v169, v178
	v_add_f32_e32 v68, v139, v68
	v_exp_f32_e32 v144, v69
	v_sub_f32_e32 v69, v170, v178
	v_add_f32_e32 v68, v141, v68
	v_exp_f32_e32 v145, v69
	v_sub_f32_e32 v69, v171, v178
	v_add_f32_e32 v68, v142, v68
	v_exp_f32_e32 v156, v69
	v_sub_f32_e32 v69, v172, v178
	v_add_f32_e32 v68, v143, v68
	v_exp_f32_e32 v157, v69
	v_sub_f32_e32 v69, v173, v178
	v_add_f32_e32 v68, v144, v68
	v_exp_f32_e32 v163, v69
	v_sub_f32_e32 v69, v174, v178
	v_add_f32_e32 v68, v145, v68
	v_exp_f32_e32 v165, v69
	v_sub_f32_e32 v69, v150, v178
	v_add_f32_e32 v68, v156, v68
	v_exp_f32_e32 v166, v69
	v_sub_f32_e32 v69, v151, v178
	v_add_f32_e32 v68, v157, v68
	v_exp_f32_e32 v167, v69
	v_sub_f32_e32 v69, v152, v178
	v_add_f32_e32 v68, v163, v68
	v_exp_f32_e32 v168, v69
	v_sub_f32_e32 v69, v153, v178
	v_add_f32_e32 v68, v165, v68
	v_exp_f32_e32 v169, v69
	v_sub_f32_e32 v69, v158, v178
	v_add_f32_e32 v68, v166, v68
	v_exp_f32_e32 v158, v69
	v_sub_f32_e32 v69, v159, v178
	v_add_f32_e32 v68, v167, v68
	v_exp_f32_e32 v159, v69
	v_sub_f32_e32 v69, v160, v178
	v_add_f32_e32 v68, v168, v68
	v_exp_f32_e32 v160, v69
	v_sub_f32_e32 v69, v161, v178
	v_add_f32_e32 v68, v169, v68
	v_exp_f32_e32 v161, v69
	v_sub_f32_e32 v69, v146, v178
	v_add_f32_e32 v68, v158, v68
	v_exp_f32_e32 v170, v69
	v_sub_f32_e32 v69, v147, v178
	v_add_f32_e32 v68, v159, v68
	v_exp_f32_e32 v171, v69
	v_sub_f32_e32 v69, v148, v178
	v_add_f32_e32 v68, v160, v68
	v_exp_f32_e32 v172, v69
	v_sub_f32_e32 v69, v149, v178
	v_add_f32_e32 v68, v161, v68
	v_exp_f32_e32 v173, v69
	v_sub_f32_e32 v69, v134, v178
	v_add_f32_e32 v68, v170, v68
	v_exp_f32_e32 v174, v69
	v_sub_f32_e32 v69, v135, v178
	v_add_f32_e32 v68, v171, v68
	v_exp_f32_e32 v179, v69
	v_sub_f32_e32 v69, v73, v178
	v_add_f32_e32 v68, v172, v68
	v_exp_f32_e32 v195, v69
	v_sub_f32_e32 v69, v74, v178
	v_add_f32_e32 v68, v173, v68
	v_exp_f32_e32 v196, v69
	v_sub_f32_e32 v69, v75, v178
	v_add_f32_e32 v68, v174, v68
	v_exp_f32_e32 v197, v69
	v_sub_f32_e32 v69, v136, v178
	v_add_f32_e32 v68, v179, v68
	v_exp_f32_e32 v198, v69
	v_add_f32_e32 v68, v195, v68
	v_add_f32_e32 v68, v196, v68
	v_add_f32_e32 v68, v197, v68
	v_add_f32_e32 v146, v198, v68
	v_sub_f32_e32 v68, v137, v178
	v_exp_f32_e32 v199, v68
	v_sub_f32_e32 v68, v138, v178
	v_add_u32_e32 v74, 0xb000, v127
	v_exp_f32_e32 v200, v68
	v_add_u32_e32 v68, 0x9000, v127
	v_cvt_pk_bf16_f32 v72, v72, v100
	ds_read_b128 v[134:137], v74 offset:256
	v_cvt_pk_bf16_f32 v74, v142, v143
	v_add_u32_e32 v100, 0xd000, v127
	v_add_u32_e32 v142, 0xf000, v127
	v_sub_f32_e32 v147, v140, v178
	ds_read_b128 v[68:71], v68
	v_cvt_pk_bf16_f32 v73, v139, v141
	v_cvt_pk_bf16_f32 v75, v144, v145
	ds_read_b128 v[138:141], v100 offset:512
	ds_read_b128 v[142:145], v142 offset:768
	s_waitcnt lgkmcnt(2)
	v_mfma_f32_16x16x32_bf16 v[68:71], v[68:71], v[72:75], 0
	v_exp_f32_e32 v100, v147
	v_add_f32_e32 v146, v199, v146
	v_add_f32_e32 v146, v200, v146
	v_mfma_f32_16x16x32_bf16 v[134:137], v[134:137], v[72:75], 0
	v_add_f32_e32 v201, v100, v146
	v_sub_f32_e32 v146, v154, v178
	v_add_u32_e32 v148, 0xb000, v130
	s_waitcnt lgkmcnt(1)
	v_mfma_f32_16x16x32_bf16 v[138:141], v[138:141], v[72:75], 0
	v_exp_f32_e32 v202, v146
	v_cvt_pk_bf16_f32 v146, v156, v157
	v_cvt_pk_bf16_f32 v147, v163, v165
	s_waitcnt lgkmcnt(0)
	v_mfma_f32_16x16x32_bf16 v[72:75], v[142:145], v[72:75], 0
	v_add_u32_e32 v142, 0x9000, v130
	ds_read_b128 v[142:145], v142
	ds_read_b128 v[150:153], v148 offset:256
	v_cvt_pk_bf16_f32 v148, v166, v167
	v_cvt_pk_bf16_f32 v149, v168, v169
	v_add_u32_e32 v154, 0xd000, v130
	s_waitcnt lgkmcnt(1)
	v_mfma_f32_16x16x32_bf16 v[68:71], v[142:145], v[146:149], v[68:71]
	v_add_u32_e32 v142, 0xf000, v130
	ds_read_b128 v[142:145], v142 offset:768
	v_sub_f32_e32 v203, v155, v178
	ds_read_b128 v[154:157], v154 offset:512
	s_waitcnt lgkmcnt(1)
	v_mfma_f32_16x16x32_bf16 v[72:75], v[142:145], v[146:149], v[72:75]
	v_add_u32_e32 v142, 0x9000, v131
	ds_read_b128 v[142:145], v142
	v_exp_f32_e32 v163, v203
	v_mfma_f32_16x16x32_bf16 v[134:137], v[150:153], v[146:149], v[134:137]
	v_sub_f32_e32 v150, v162, v178
	v_exp_f32_e32 v162, v150
	v_add_f32_e32 v150, v202, v201
	s_waitcnt lgkmcnt(1)
	v_mfma_f32_16x16x32_bf16 v[138:141], v[154:157], v[146:149], v[138:141]
	v_add_f32_e32 v150, v163, v150
	v_add_u32_e32 v148, 0xb000, v131
	v_add_f32_e32 v165, v162, v150
	v_cvt_pk_bf16_f32 v146, v158, v159
	v_cvt_pk_bf16_f32 v147, v160, v161
	ds_read_b128 v[150:153], v148 offset:256
	v_cvt_pk_bf16_f32 v148, v170, v171
	v_cvt_pk_bf16_f32 v149, v172, v173
	v_add_u32_e32 v154, 0xd000, v131
	s_waitcnt lgkmcnt(1)
	v_mfma_f32_16x16x32_bf16 v[68:71], v[142:145], v[146:149], v[68:71]
	v_add_u32_e32 v142, 0xf000, v131
	ds_read_b128 v[142:145], v142 offset:768
	ds_read_b128 v[154:157], v154 offset:512
	s_waitcnt lgkmcnt(1)
	v_mfma_f32_16x16x32_bf16 v[72:75], v[142:145], v[146:149], v[72:75]
	v_add_u32_e32 v142, 0x9000, v132
	ds_read_b128 v[142:145], v142
	v_sub_f32_e32 v164, v164, v178
	v_mfma_f32_16x16x32_bf16 v[134:137], v[150:153], v[146:149], v[134:137]
	v_sub_f32_e32 v150, v175, v178
	v_exp_f32_e32 v160, v150
	v_sub_f32_e32 v150, v176, v178
	s_waitcnt lgkmcnt(1)
	v_mfma_f32_16x16x32_bf16 v[138:141], v[154:157], v[146:149], v[138:141]
	v_add_u32_e32 v148, 0xb000, v132
	v_exp_f32_e32 v161, v150
	ds_read_b128 v[150:153], v148 offset:256
	v_exp_f32_e32 v158, v164
	v_sub_f32_e32 v164, v177, v178
	v_exp_f32_e32 v164, v164
	v_cvt_pk_bf16_f32 v146, v174, v179
	v_add_f32_e32 v159, v158, v165
	v_cvt_pk_bf16_f32 v147, v195, v196
	v_cvt_pk_bf16_f32 v148, v197, v198
	v_cvt_pk_bf16_f32 v149, v199, v200
	v_add_u32_e32 v154, 0xd000, v132
	s_waitcnt lgkmcnt(1)
	v_mfma_f32_16x16x32_bf16 v[68:71], v[142:145], v[146:149], v[68:71]
	v_add_f32_e32 v142, v160, v159
	v_add_f32_e32 v142, v161, v142
	ds_read_b128 v[154:157], v154 offset:512
	s_waitcnt lgkmcnt(1)
	v_mfma_f32_16x16x32_bf16 v[134:137], v[150:153], v[146:149], v[134:137]
	v_add_f32_e32 v150, v164, v142
	v_add_u32_e32 v142, 0xf000, v132
	ds_read_b128 v[142:145], v142 offset:768
	ds_bpermute_b32 v151, v128, v150
	s_waitcnt lgkmcnt(1)
	v_mfma_f32_16x16x32_bf16 v[72:75], v[142:145], v[146:149], v[72:75]
	v_add_u32_e32 v142, 0x9000, v133
	ds_read_b128 v[142:145], v142
	s_waitcnt lgkmcnt(1)
	v_add_f32_e32 v159, v150, v151
	v_mfma_f32_16x16x32_bf16 v[138:141], v[154:157], v[146:149], v[138:141]
	ds_bpermute_b32 v165, v113, v159
	v_cvt_pk_bf16_f32 v146, v100, v202
	v_add_u32_e32 v100, 0xb000, v133
	ds_read_b128 v[150:153], v100 offset:256
	v_add_u32_e32 v100, 0xd000, v133
	v_fma_f32 v99, v99, s4, -v178
	ds_read_b128 v[154:157], v100 offset:512
	v_add_u32_e32 v100, 0xf000, v133
	v_exp_f32_e32 v99, v99
	v_cvt_pk_bf16_f32 v147, v163, v162
	v_cvt_pk_bf16_f32 v148, v158, v160
	v_cvt_pk_bf16_f32 v149, v161, v164
	v_writelane_b32 v244, s90, 62
	s_waitcnt lgkmcnt(3)
	v_mfma_f32_16x16x32_bf16 v[68:71], v[142:145], v[146:149], v[68:71]
	ds_read_b128 v[142:145], v100 offset:768
	s_waitcnt lgkmcnt(3)
	v_add_f32_e32 v100, v159, v165
	v_add_f32_e32 v99, v99, v100
	v_rcp_f32_e32 v100, v99
	s_waitcnt lgkmcnt(2)
	v_mfma_f32_16x16x32_bf16 v[134:137], v[150:153], v[146:149], v[134:137]
	v_lshl_add_u32 v99, s90, 7, v109
	s_mov_b32 s16, 0xf149f2ca
	v_pk_mul_f32 v[70:71], v[70:71], v[100:101] op_sel_hi:[1,0]
	s_waitcnt lgkmcnt(1)
	v_mfma_f32_16x16x32_bf16 v[138:141], v[154:157], v[146:149], v[138:141]
	v_mul_f32_e64 v68, v68, v100
	v_mul_f32_e64 v69, v69, v100
	s_nop 0
	v_pk_mul_f32 v[134:135], v[134:135], v[100:101] op_sel_hi:[1,0]
	v_writelane_b32 v244, s91, 63
	s_waitcnt lgkmcnt(0)
	v_mfma_f32_16x16x32_bf16 v[72:75], v[142:145], v[146:149], v[72:75]
	v_mul_f32_e64 v142, v70, v70
	v_mul_f32_e64 v143, v71, v71
	v_pk_mul_f32 v[144:145], v[68:69], v[68:69]
	v_cvt_pk_bf16_f32 v68, v68, v69
	v_cvt_pk_bf16_f32 v69, v70, v71
	v_pk_mul_f32 v[70:71], v[136:137], v[100:101] op_sel_hi:[1,0]
	v_pk_mov_b32 v[146:147], v[144:145], v[142:143] op_sel:[1,0]
	v_mov_b32_e32 v145, v143
	v_pk_add_f32 v[142:143], v[146:147], v[144:145]
	v_pk_mul_f32 v[136:137], v[70:71], v[70:71]
	v_add_f32_e32 v142, v142, v143
	v_pk_mul_f32 v[144:145], v[134:135], v[134:135]
	v_cvt_pk_bf16_f32 v134, v134, v135
	v_cvt_pk_bf16_f32 v135, v70, v71
	v_pk_mul_f32 v[70:71], v[138:139], v[100:101] op_sel_hi:[1,0]
	v_add_f32_e32 v143, v110, v142
	v_pk_mov_b32 v[146:147], v[144:145], v[136:137] op_sel:[1,0]
	v_mov_b32_e32 v145, v137
	ds_write2_b64 v99, v[68:69], v[134:135] offset1:4
	v_pk_mul_f32 v[68:69], v[140:141], v[100:101] op_sel_hi:[1,0]
	v_mul_f32_e32 v110, v70, v70
	v_pk_add_f32 v[136:137], v[146:147], v[144:145]
	v_pk_fma_f32 v[134:135], v[70:71], v[70:71], v[110:111] op_sel_hi:[1,1,0]
	v_mul_f32_e32 v110, v68, v68
	v_pk_add_f32 v[136:137], v[136:137], v[136:137] op_sel_hi:[0,1]
	v_pk_fma_f32 v[138:139], v[68:69], v[68:69], v[110:111] op_sel_hi:[1,1,0]
	v_cvt_pk_bf16_f32 v70, v70, v71
	v_cvt_pk_bf16_f32 v71, v68, v69
	v_pk_mul_f32 v[68:69], v[74:75], v[100:101] op_sel_hi:[1,0]
	v_pk_mul_f32 v[72:73], v[72:73], v[100:101] op_sel_hi:[1,0]
	v_mul_f32_e32 v136, v68, v68
	v_mul_f32_e32 v134, v72, v72
	v_mul_f32_e32 v138, v73, v73
	v_mul_f32_e32 v142, v69, v69
	v_pk_add_f32 v[74:75], v[134:135], v[138:139]
	v_pk_add_f32 v[134:135], v[136:137], v[142:143]
	s_and_b64 vcc, exec, s[2:3]
	v_pk_add_f32 v[74:75], v[74:75], v[134:135]
	s_mov_b32 s90, 1
	v_add_f32_e32 v110, v74, v75
	s_mov_b64 s[2:3], 0
	v_cvt_pk_bf16_f32 v72, v72, v73
	v_cvt_pk_bf16_f32 v73, v68, v69
	ds_write2_b64 v99, v[70:71], v[72:73] offset0:8 offset1:12
	s_cbranch_vccnz .LBB0_181
.LBB0_190:
	v_lshlrev_b32_e32 v100, 16, v36
	v_and_b32_e32 v99, 0xffff0000, v36
	v_lshlrev_b32_e32 v134, 16, v40
	v_and_b32_e32 v135, 0xffff0000, v40
	v_mul_f32_e32 v68, v100, v100
	v_mul_f32_e32 v140, v99, v99
	v_lshlrev_b32_e32 v75, 16, v37
	v_fmac_f32_e32 v68, v134, v134
	v_fmac_f32_e32 v140, v135, v135
	v_lshlrev_b32_e32 v136, 16, v41
	v_add_f32_e32 v68, v68, v140
	v_mul_f32_e32 v140, v75, v75
	v_and_b32_e32 v74, 0xffff0000, v37
	v_fmac_f32_e32 v140, v136, v136
	v_and_b32_e32 v137, 0xffff0000, v41
	v_add_f32_e32 v68, v140, v68
	v_mul_f32_e32 v140, v74, v74
	v_lshlrev_b32_e32 v73, 16, v38
	v_fmac_f32_e32 v140, v137, v137
	v_lshlrev_b32_e32 v138, 16, v42
	v_add_f32_e32 v68, v140, v68
	v_mul_f32_e32 v140, v73, v73
	v_and_b32_e32 v72, 0xffff0000, v38
	v_fmac_f32_e32 v140, v138, v138
	v_and_b32_e32 v139, 0xffff0000, v42
	v_add_f32_e32 v68, v140, v68
	v_mul_f32_e32 v140, v72, v72
	v_lshlrev_b32_e32 v71, 16, v39
	v_fmac_f32_e32 v140, v139, v139
	v_lshlrev_b32_e32 v142, 16, v43
	v_add_f32_e32 v68, v140, v68
	v_mul_f32_e32 v140, v71, v71
	v_and_b32_e32 v70, 0xffff0000, v39
	v_fmac_f32_e32 v140, v142, v142
	v_and_b32_e32 v69, 0xffff0000, v43
	v_add_f32_e32 v68, v140, v68
	v_mul_f32_e32 v140, v70, v70
	v_fmac_f32_e32 v140, v69, v69
	v_add_f32_e32 v68, v140, v68
	v_mov_b32_e32 v140, v68
	s_nop 1
	v_permlane16_swap_b32 v140, v68
	v_mov_b32_e32 v141, v241
	s_waitcnt lgkmcnt(0)
	v_add_f32_e32 v145, v68, v140
	v_mov_b32_e32 v146, v145
	s_nop 1
	v_permlane32_swap_b32 v146, v145
	v_mov_b32_e32 v140, v240
	v_mov_b32_e32 v143, v242
	v_mov_b32_e32 v144, v245
	v_mov_b32_e32 v147, v246
	v_mov_b32_e32 v148, v247
	v_mov_b32_e32 v149, v217
	v_mov_b32_e32 v68, v219
	s_waitcnt lgkmcnt(0)
	v_add_f32_e32 v145, v145, v146
	v_fmamk_f32 v145, v145, 0x3c800000, v180
	v_rsq_f32_e32 v145, v145
	v_lshlrev_b32_e32 v146, 16, v47
	v_readlane_b32 s4, v244, 62
	v_readlane_b32 s5, v244, 63
	v_mul_f32_e32 v145, 0x3e38aa3b, v145
	v_mul_f32_e32 v146, v145, v146
	v_mul_f32_e32 v142, v145, v142
	s_waitcnt vmcnt(0)
	v_mul_f32_e32 v146, v146, v77
	v_mul_f32_e32 v142, v230, v142
	v_mul_f32_e32 v146, v108, v146
	v_fmac_f32_e32 v146, v142, v149
	v_and_b32_e32 v142, 0xffff0000, v46
	v_mul_f32_e32 v142, v145, v142
	v_mul_f32_e32 v139, v145, v139
	v_mul_f32_e32 v142, v142, v76
	v_mul_f32_e32 v139, v229, v139
	v_mul_f32_e32 v142, v107, v142
	v_fmac_f32_e32 v142, v139, v148
	v_lshlrev_b32_e32 v139, 16, v46
	v_mul_f32_e32 v139, v145, v139
	v_mul_f32_e32 v138, v145, v138
	v_mul_f32_e32 v139, v139, v67
	v_mul_f32_e32 v138, v228, v138
	v_mul_f32_e32 v139, v106, v139
	v_fmac_f32_e32 v139, v138, v147
	v_and_b32_e32 v138, 0xffff0000, v45
	v_mul_f32_e32 v138, v145, v138
	v_mul_f32_e32 v137, v145, v137
	v_mul_f32_e32 v138, v138, v66
	v_mul_f32_e32 v137, v227, v137
	v_mul_f32_e32 v138, v105, v138
	v_fmac_f32_e32 v138, v137, v144
	v_lshlrev_b32_e32 v137, 16, v45
	v_mul_f32_e32 v137, v145, v137
	v_mul_f32_e32 v136, v145, v136
	v_mul_f32_e32 v137, v137, v65
	v_mul_f32_e32 v136, v226, v136
	v_mul_f32_e32 v137, v104, v137
	v_fmac_f32_e32 v137, v136, v143
	v_and_b32_e32 v136, 0xffff0000, v44
	v_mul_f32_e32 v136, v145, v136
	v_mul_f32_e32 v135, v145, v135
	v_mul_f32_e32 v136, v136, v64
	v_mul_f32_e32 v135, v225, v135
	v_mul_f32_e32 v136, v103, v136
	v_fmac_f32_e32 v136, v135, v141
	v_lshlrev_b32_e32 v135, 16, v44
	v_mul_f32_e32 v135, v145, v135
	v_mul_f32_e32 v134, v145, v134
	v_mul_f32_e32 v135, v135, v79
	v_mul_f32_e32 v134, v224, v134
	v_mul_f32_e32 v135, v102, v135
	v_mul_f32_e32 v100, v145, v100
	v_mul_f32_e32 v69, v145, v69
	v_fmac_f32_e32 v135, v134, v140
	v_mul_f32_e32 v134, v232, v100
	v_mul_f32_e32 v100, v231, v69
	v_mul_f32_e32 v69, v145, v70
	v_mul_f32_e32 v147, v239, v69
	v_and_b32_e32 v69, 0xffff0000, v47
	v_mul_f32_e32 v69, v145, v69
	v_mul_f32_e32 v69, v69, v78
	v_mul_f32_e32 v71, v145, v71
	v_pk_mul_f32 v[68:69], v[100:101], v[68:69]
	s_or_b32 s90, s90, s33
	v_mul_f32_e32 v99, v145, v99
	v_mul_f32_e32 v75, v145, v75
	v_mul_f32_e32 v74, v145, v74
	v_mul_f32_e32 v73, v145, v73
	v_mul_f32_e32 v72, v145, v72
	v_mul_f32_e32 v71, v238, v71
	v_add_f32_e32 v68, v68, v69
	s_mov_b32 s91, s5
	s_cmp_eq_u32 s90, 3
	v_mul_f32_e32 v99, v233, v99
	v_mul_f32_e32 v140, v234, v75
	v_mul_f32_e32 v141, v235, v74
	v_mul_f32_e32 v143, v236, v73
	v_mul_f32_e32 v144, v237, v72
	v_cvt_pk_bf16_f32 v72, v135, v136
	v_cvt_pk_bf16_f32 v73, v137, v138
	v_cvt_pk_bf16_f32 v74, v139, v142
	v_cvt_pk_bf16_f32 v75, v146, v68
	v_cvt_pk_bf16_f32 v68, v134, v99
	v_cvt_pk_bf16_f32 v69, v140, v141
	v_cvt_pk_bf16_f32 v70, v143, v144
	v_cvt_pk_bf16_f32 v71, v71, v147
	s_cbranch_scc1 .LBB0_189
	s_lshl_b32 s94, s90, 7
	s_mov_b32 s95, s91
	v_lshl_add_u64 v[36:37], v[82:83], 0, s[94:95]
	v_mov_b32_e32 v99, v3
	v_lshl_add_u64 v[44:45], v[36:37], 0, v[2:3]
	v_lshl_add_u64 v[40:41], v[36:37], 0, v[98:99]
	global_load_dwordx4 v[36:39], v[40:41], off offset:2240
	s_nop 0
	global_load_dwordx4 v[40:43], v[40:41], off offset:2176
	s_nop 0
	global_load_dwordx4 v[44:47], v[44:45], off offset:2176
	s_branch .LBB0_189
.LBB0_208:
	s_waitcnt vmcnt(0)
	v_lshlrev_b32_e32 v2, 1, v111
	v_lshl_add_u64 v[14:15], v[82:83], 0, v[2:3]
	global_load_dwordx2 v[20:21], v[14:15], off offset:3072
	v_readlane_b32 s8, v244, 0
	v_lshlrev_b32_e32 v18, 2, v111
	v_readlane_b32 s12, v244, 4
	v_readlane_b32 s13, v244, 5
	v_mov_b32_e32 v16, v110
	s_nop 1
	v_permlane16_swap_b32 v16, v110
	v_readlane_b32 s4, v244, 57
	v_lshlrev_b64 v[12:13], 11, v[80:81]
	v_readlane_b32 s6, v244, 59
	v_readlane_b32 s7, v244, 60
	global_load_dwordx4 v[8:11], v18, s[12:13] offset:2048
	global_load_dwordx2 v[46:47], v[14:15], off offset:3104
	global_load_dwordx2 v[52:53], v[14:15], off offset:3136
	global_load_dwordx2 v[54:55], v[14:15], off offset:3168
	global_load_dwordx4 v[56:59], v18, s[12:13] offset:2112
	global_load_dwordx4 v[60:63], v18, s[12:13] offset:2176
	global_load_dwordx4 v[64:67], v18, s[12:13] offset:2240
	global_load_dwordx2 v[68:69], v[14:15], off offset:3200
	global_load_dwordx4 v[70:73], v18, s[12:13] offset:2304
	global_load_dwordx2 v[74:75], v[14:15], off offset:3232
	global_load_dwordx2 v[76:77], v[14:15], off offset:3264
	global_load_dwordx2 v[78:79], v[14:15], off offset:3296
	global_load_dwordx4 v[84:87], v18, s[12:13] offset:2368
	global_load_dwordx4 v[88:91], v18, s[12:13] offset:2432
	global_load_dwordx4 v[92:95], v18, s[12:13] offset:2496
	global_load_dwordx2 v[96:97], v[14:15], off offset:3328
	global_load_dwordx4 v[98:101], v18, s[12:13] offset:2560
	global_load_dwordx2 v[102:103], v[14:15], off offset:3360
	global_load_dwordx2 v[104:105], v[14:15], off offset:3392
	global_load_dwordx2 v[106:107], v[14:15], off offset:3424
	global_load_dwordx4 v[116:119], v18, s[12:13] offset:2624
	global_load_dwordx4 v[120:123], v18, s[12:13] offset:2688
	global_load_dwordx4 v[124:127], v18, s[12:13] offset:2752
	global_load_dwordx2 v[132:133], v[14:15], off offset:3456
	global_load_dwordx4 v[134:137], v18, s[12:13] offset:2816
	global_load_dwordx2 v[138:139], v[14:15], off offset:3488
	global_load_dwordx2 v[140:141], v[14:15], off offset:3520
	global_load_dwordx2 v[142:143], v[14:15], off offset:3552
	global_load_dwordx4 v[144:147], v18, s[12:13] offset:2880
	global_load_dwordx4 v[148:151], v18, s[12:13] offset:2944
	global_load_dwordx4 v[152:155], v18, s[12:13] offset:3008
	s_waitcnt lgkmcnt(0)
	v_add_f32_e32 v19, v110, v16
	v_mov_b32_e32 v28, v19
	s_nop 1
	v_permlane32_swap_b32 v28, v19
	s_mov_b64 s[0:1], 0xdde0400
	v_lshl_add_u64 v[12:13], s[6:7], 0, v[12:13]
	v_lshl_add_u64 v[12:13], v[12:13], 0, s[0:1]
	s_mov_b32 s0, 0x800000
	s_waitcnt lgkmcnt(0)
	v_add_f32_e32 v19, v19, v28
	v_fmamk_f32 v19, v19, 0x3b800000, v180
	v_mul_f32_e32 v28, 0x4b800000, v19
	v_cmp_gt_f32_e32 vcc, s0, v19
	ds_read2_b64 v[4:7], v109 offset1:4
	v_cndmask_b32_e32 v19, v19, v28, vcc
	v_rsq_f32_e32 v19, v19
	v_lshl_add_u64 v[26:27], v[12:13], 0, v[2:3]
	s_waitcnt lgkmcnt(0)
	v_lshlrev_b32_e32 v29, 16, v4
	v_and_b32_e32 v31, 0xffff0000, v4
	v_mul_f32_e32 v4, 0x45800000, v19
	v_lshlrev_b32_e32 v33, 16, v5
	v_and_b32_e32 v35, 0xffff0000, v5
	v_cndmask_b32_e32 v5, v19, v4, vcc
	v_mov_b32_e32 v38, v5
	v_mov_b32_e32 v40, v5
	v_mov_b32_e32 v42, v5
	v_readlane_b32 s88, v243, 5
	v_readlane_b32 s20, v243, 30
	v_readlane_b32 s89, v243, 6
	v_readlane_b32 s0, v243, 8
	v_mov_b32_e32 v45, v3
	v_mov_b32_e32 v115, v3
	v_readlane_b32 s2, v244, 62
	v_readlane_b32 s10, v244, 2
	v_readlane_b32 s11, v244, 3
	v_mov_b32_e32 v51, v3
	v_readlane_b32 s9, v244, 1
	v_readlane_b32 s3, v244, 63
	v_readlane_b32 s14, v244, 6
	v_readlane_b32 s15, v244, 7
	v_readlane_b32 s5, v244, 58
	v_readlane_b32 s86, v243, 3
	v_readlane_b32 s22, v243, 28
	v_mov_b32_e32 v130, 0
	s_mov_b64 s[4:5], 0
	v_readlane_b32 s58, v243, 2
	v_readlane_b32 s87, v243, 4
	s_movk_i32 s84, 0x7f
	v_readlane_b32 s23, v243, 29
	v_readlane_b32 s21, v243, 31
	s_waitcnt vmcnt(31)
	v_lshlrev_b32_e32 v28, 16, v20
	v_mul_f32_e32 v4, 0xbfb8aa3b, v28
	v_exp_f32_e32 v4, v4
	v_and_b32_e32 v30, 0xffff0000, v20
	v_mul_f32_e32 v19, 0xbfb8aa3b, v30
	v_exp_f32_e32 v19, v19
	v_add_f32_e32 v4, 1.0, v4
	v_rcp_f32_e32 v4, v4
	v_lshlrev_b32_e32 v32, 16, v21
	v_and_b32_e32 v34, 0xffff0000, v21
	v_mul_f32_e32 v20, 0xbfb8aa3b, v32
	v_mul_f32_e32 v21, 0xbfb8aa3b, v34
	v_exp_f32_e32 v36, v20
	v_add_f32_e32 v19, 1.0, v19
	v_exp_f32_e32 v37, v21
	v_pk_mul_f32 v[20:21], v[4:5], v[28:29]
	v_rcp_f32_e32 v4, v19
	v_add_f32_e32 v19, 1.0, v36
	s_waitcnt vmcnt(30)
	v_mul_f32_e32 v8, v8, v21
	v_add_f32_e32 v36, 1.0, v37
	v_pk_mul_f32 v[28:29], v[4:5], v[30:31]
	v_rcp_f32_e32 v4, v19
	v_mul_f32_e32 v19, v20, v8
	v_mul_f32_e32 v8, v9, v29
	v_mul_f32_e32 v20, v28, v8
	v_pk_mul_f32 v[8:9], v[4:5], v[32:33]
	v_rcp_f32_e32 v4, v36
	v_mul_f32_e32 v9, v10, v9
	v_mul_f32_e32 v10, v8, v9
	v_cvt_pk_bf16_f32 v20, v19, v20
	v_pk_mul_f32 v[8:9], v[4:5], v[34:35]
	v_lshlrev_b32_e32 v28, 16, v7
	v_mul_f32_e32 v4, v11, v9
	v_mul_f32_e32 v4, v8, v4
	v_cvt_pk_bf16_f32 v21, v10, v4
	global_store_dwordx2 v[26:27], v[20:21], off
	v_and_b32_e32 v30, 0xffff0000, v7
	s_waitcnt vmcnt(30)
	v_lshlrev_b32_e32 v27, 16, v46
	v_and_b32_e32 v7, 0xffff0000, v46
	v_lshlrev_b32_e32 v29, 16, v47
	v_and_b32_e32 v31, 0xffff0000, v47
	v_mul_f32_e32 v4, 0xbfb8aa3b, v27
	v_mul_f32_e32 v19, 0xbfb8aa3b, v7
	v_mul_f32_e32 v22, 0xbfb8aa3b, v29
	v_mul_f32_e32 v23, 0xbfb8aa3b, v31
	v_exp_f32_e32 v4, v4
	v_exp_f32_e32 v19, v19
	v_exp_f32_e32 v22, v22
	v_exp_f32_e32 v23, v23
	v_add_f32_e32 v4, 1.0, v4
	v_add_f32_e32 v19, 1.0, v19
	v_add_f32_e32 v22, 1.0, v22
	v_add_f32_e32 v23, 1.0, v23
	v_rcp_f32_e32 v33, v4
	v_rcp_f32_e32 v35, v19
	v_rcp_f32_e32 v37, v22
	v_rcp_f32_e32 v39, v23
	v_lshlrev_b32_e32 v26, 16, v6
	v_and_b32_e32 v6, 0xffff0000, v6
	v_mov_b32_e32 v32, v5
	v_mov_b32_e32 v34, v5
	v_mov_b32_e32 v36, v5
	v_pk_mul_f32 v[22:23], v[32:33], v[26:27]
	v_pk_mul_f32 v[6:7], v[34:35], v[6:7]
	v_pk_mul_f32 v[26:27], v[36:37], v[28:29]
	v_mov_b32_e32 v21, v3
	v_or_b32_e32 v20, 32, v2
	v_pk_mul_f32 v[28:29], v[38:39], v[30:31]
	v_lshl_add_u64 v[20:21], v[12:13], 0, v[20:21]
	s_waitcnt vmcnt(29)
	v_and_b32_e32 v31, 0xffff0000, v53
	s_waitcnt vmcnt(27)
	v_mul_f32_e32 v4, v56, v22
	v_mul_f32_e32 v6, v57, v6
	v_mul_f32_e32 v8, v58, v26
	v_mul_f32_e32 v9, v59, v28
	v_mul_f32_e32 v6, v6, v7
	v_mul_f32_e32 v7, v8, v27
	v_mul_f32_e32 v4, v4, v23
	v_mul_f32_e32 v8, v9, v29
	v_cvt_pk_bf16_f32 v6, v4, v6
	v_cvt_pk_bf16_f32 v7, v7, v8
	global_store_dwordx2 v[20:21], v[6:7], off
	ds_read2_b64 v[20:23], v109 offset0:8 offset1:12
	v_lshlrev_b32_e32 v27, 16, v52
	v_lshlrev_b32_e32 v29, 16, v53
	v_mul_f32_e32 v4, 0xbfb8aa3b, v27
	v_mul_f32_e32 v25, 0xbfb8aa3b, v31
	s_waitcnt lgkmcnt(0)
	v_lshlrev_b32_e32 v28, 16, v21
	v_and_b32_e32 v30, 0xffff0000, v21
	v_and_b32_e32 v21, 0xffff0000, v52
	v_mul_f32_e32 v19, 0xbfb8aa3b, v21
	v_mul_f32_e32 v24, 0xbfb8aa3b, v29
	v_exp_f32_e32 v4, v4
	v_exp_f32_e32 v19, v19
	v_exp_f32_e32 v24, v24
	v_exp_f32_e32 v25, v25
	v_add_f32_e32 v4, 1.0, v4
	v_add_f32_e32 v19, 1.0, v19
	v_add_f32_e32 v24, 1.0, v24
	v_add_f32_e32 v25, 1.0, v25
	v_rcp_f32_e32 v33, v4
	v_rcp_f32_e32 v35, v19
	v_rcp_f32_e32 v37, v24
	v_rcp_f32_e32 v39, v25
	v_lshlrev_b32_e32 v26, 16, v20
	v_and_b32_e32 v20, 0xffff0000, v20
	v_pk_mul_f32 v[24:25], v[32:33], v[26:27]
	v_pk_mul_f32 v[20:21], v[34:35], v[20:21]
	v_pk_mul_f32 v[26:27], v[36:37], v[28:29]
	v_mov_b32_e32 v11, v3
	v_or_b32_e32 v10, 64, v2
	v_pk_mul_f32 v[28:29], v[38:39], v[30:31]
	v_lshl_add_u64 v[10:11], v[12:13], 0, v[10:11]
	v_mov_b32_e32 v30, v5
	s_waitcnt vmcnt(27)
	v_mul_f32_e32 v4, v60, v24
	v_mul_f32_e32 v6, v61, v20
	v_mul_f32_e32 v7, v62, v26
	v_mul_f32_e32 v8, v63, v28
	v_mul_f32_e32 v6, v6, v21
	v_mul_f32_e32 v7, v7, v27
	v_mul_f32_e32 v4, v4, v25
	v_mul_f32_e32 v8, v8, v29
	v_cvt_pk_bf16_f32 v6, v4, v6
	v_cvt_pk_bf16_f32 v7, v7, v8
	global_store_dwordx2 v[10:11], v[6:7], off
	v_lshlrev_b32_e32 v26, 16, v23
	v_and_b32_e32 v28, 0xffff0000, v23
	v_lshlrev_b32_e32 v21, 16, v54
	v_and_b32_e32 v23, 0xffff0000, v54
	v_lshlrev_b32_e32 v27, 16, v55
	v_and_b32_e32 v29, 0xffff0000, v55
	v_mul_f32_e32 v4, 0xbfb8aa3b, v21
	v_mul_f32_e32 v16, 0xbfb8aa3b, v23
	v_mul_f32_e32 v17, 0xbfb8aa3b, v27
	v_mul_f32_e32 v19, 0xbfb8aa3b, v29
	v_exp_f32_e32 v4, v4
	v_exp_f32_e32 v16, v16
	v_exp_f32_e32 v17, v17
	v_exp_f32_e32 v19, v19
	v_add_f32_e32 v4, 1.0, v4
	v_add_f32_e32 v16, 1.0, v16
	v_add_f32_e32 v17, 1.0, v17
	v_add_f32_e32 v19, 1.0, v19
	v_rcp_f32_e32 v31, v4
	v_rcp_f32_e32 v33, v16
	v_rcp_f32_e32 v35, v17
	v_rcp_f32_e32 v37, v19
	v_lshlrev_b32_e32 v20, 16, v22
	v_and_b32_e32 v22, 0xffff0000, v22
	v_pk_mul_f32 v[16:17], v[30:31], v[20:21]
	v_pk_mul_f32 v[20:21], v[32:33], v[22:23]
	v_pk_mul_f32 v[22:23], v[34:35], v[26:27]
	v_mov_b32_e32 v11, v3
	v_or_b32_e32 v10, 0x60, v2
	v_pk_mul_f32 v[26:27], v[36:37], v[28:29]
	v_lshl_add_u64 v[10:11], v[12:13], 0, v[10:11]
	s_waitcnt vmcnt(27)
	v_mul_f32_e32 v4, v64, v16
	v_mul_f32_e32 v6, v65, v20
	v_mul_f32_e32 v7, v66, v22
	v_mul_f32_e32 v8, v67, v26
	v_mul_f32_e32 v6, v6, v21
	v_mul_f32_e32 v7, v7, v23
	v_mul_f32_e32 v4, v4, v17
	v_mul_f32_e32 v8, v8, v27
	v_cvt_pk_bf16_f32 v6, v4, v6
	v_cvt_pk_bf16_f32 v7, v7, v8
	global_store_dwordx2 v[10:11], v[6:7], off
	ds_read2_b64 v[20:23], v109 offset0:16 offset1:20
	s_waitcnt vmcnt(27)
	v_lshlrev_b32_e32 v31, 16, v68
	v_lshlrev_b32_e32 v33, 16, v69
	v_and_b32_e32 v35, 0xffff0000, v69
	s_waitcnt lgkmcnt(0)
	v_lshlrev_b32_e32 v32, 16, v21
	v_and_b32_e32 v34, 0xffff0000, v21
	v_and_b32_e32 v21, 0xffff0000, v68
	v_mul_f32_e32 v4, 0xbfb8aa3b, v31
	v_mul_f32_e32 v19, 0xbfb8aa3b, v21
	v_mul_f32_e32 v24, 0xbfb8aa3b, v33
	v_mul_f32_e32 v25, 0xbfb8aa3b, v35
	v_exp_f32_e32 v4, v4
	v_exp_f32_e32 v19, v19
	v_exp_f32_e32 v24, v24
	v_exp_f32_e32 v25, v25
	v_add_f32_e32 v4, 1.0, v4
	v_add_f32_e32 v19, 1.0, v19
	v_add_f32_e32 v24, 1.0, v24
	v_add_f32_e32 v25, 1.0, v25
	v_rcp_f32_e32 v37, v4
	v_rcp_f32_e32 v39, v19
	v_rcp_f32_e32 v41, v24
	v_rcp_f32_e32 v43, v25
	v_lshlrev_b32_e32 v30, 16, v20
	v_and_b32_e32 v20, 0xffff0000, v20
	v_pk_mul_f32 v[24:25], v[36:37], v[30:31]
	v_pk_mul_f32 v[20:21], v[38:39], v[20:21]
	v_pk_mul_f32 v[30:31], v[40:41], v[32:33]
	v_mov_b32_e32 v17, v3
	v_or_b32_e32 v16, 0x80, v2
	v_pk_mul_f32 v[32:33], v[42:43], v[34:35]
	v_lshl_add_u64 v[16:17], v[12:13], 0, v[16:17]
	v_mov_b32_e32 v34, v5
	s_waitcnt vmcnt(26)
	v_mul_f32_e32 v4, v70, v24
	v_mul_f32_e32 v8, v71, v20
	v_mul_f32_e32 v9, v72, v30
	v_mul_f32_e32 v10, v73, v32
	v_mul_f32_e32 v8, v8, v21
	v_mul_f32_e32 v9, v9, v31
	v_mul_f32_e32 v4, v4, v25
	v_mul_f32_e32 v10, v10, v33
	v_cvt_pk_bf16_f32 v8, v4, v8
	v_cvt_pk_bf16_f32 v9, v9, v10
	global_store_dwordx2 v[16:17], v[8:9], off
	v_lshlrev_b32_e32 v24, 16, v23
	v_and_b32_e32 v30, 0xffff0000, v23
	s_waitcnt vmcnt(26)
	v_lshlrev_b32_e32 v21, 16, v74
	v_and_b32_e32 v23, 0xffff0000, v74
	v_lshlrev_b32_e32 v25, 16, v75
	v_and_b32_e32 v31, 0xffff0000, v75
	v_mul_f32_e32 v4, 0xbfb8aa3b, v21
	v_mul_f32_e32 v19, 0xbfb8aa3b, v23
	v_mul_f32_e32 v26, 0xbfb8aa3b, v25
	v_mul_f32_e32 v27, 0xbfb8aa3b, v31
	v_exp_f32_e32 v4, v4
	v_exp_f32_e32 v19, v19
	v_exp_f32_e32 v26, v26
	v_exp_f32_e32 v27, v27
	v_add_f32_e32 v4, 1.0, v4
	v_add_f32_e32 v19, 1.0, v19
	v_add_f32_e32 v26, 1.0, v26
	v_add_f32_e32 v27, 1.0, v27
	v_rcp_f32_e32 v33, v4
	v_rcp_f32_e32 v35, v19
	v_rcp_f32_e32 v37, v26
	v_rcp_f32_e32 v39, v27
	v_lshlrev_b32_e32 v20, 16, v22
	v_and_b32_e32 v22, 0xffff0000, v22
	v_mov_b32_e32 v32, v5
	v_pk_mul_f32 v[20:21], v[32:33], v[20:21]
	v_pk_mul_f32 v[22:23], v[34:35], v[22:23]
	v_pk_mul_f32 v[24:25], v[36:37], v[24:25]
	v_mov_b32_e32 v17, v3
	v_or_b32_e32 v16, 0xa0, v2
	v_pk_mul_f32 v[26:27], v[38:39], v[30:31]
	v_lshl_add_u64 v[16:17], v[12:13], 0, v[16:17]
	s_waitcnt vmcnt(25)
	v_and_b32_e32 v31, 0xffff0000, v77
	s_waitcnt vmcnt(23)
	v_mul_f32_e32 v4, v84, v20
	v_mul_f32_e32 v8, v85, v22
	v_mul_f32_e32 v9, v86, v24
	v_mul_f32_e32 v10, v87, v26
	v_mul_f32_e32 v8, v8, v23
	v_mul_f32_e32 v9, v9, v25
	v_mul_f32_e32 v4, v4, v21
	v_mul_f32_e32 v10, v10, v27
	v_cvt_pk_bf16_f32 v8, v4, v8
	v_cvt_pk_bf16_f32 v9, v9, v10
	global_store_dwordx2 v[16:17], v[8:9], off
	ds_read2_b64 v[20:23], v109 offset0:24 offset1:28
	v_lshlrev_b32_e32 v25, 16, v76
	v_lshlrev_b32_e32 v27, 16, v77
	v_mul_f32_e32 v4, 0xbfb8aa3b, v25
	v_mul_f32_e32 v29, 0xbfb8aa3b, v31
	s_waitcnt lgkmcnt(0)
	v_lshlrev_b32_e32 v26, 16, v21
	v_and_b32_e32 v30, 0xffff0000, v21
	v_and_b32_e32 v21, 0xffff0000, v76
	v_mul_f32_e32 v19, 0xbfb8aa3b, v21
	v_mul_f32_e32 v28, 0xbfb8aa3b, v27
	v_exp_f32_e32 v4, v4
	v_exp_f32_e32 v19, v19
	v_exp_f32_e32 v28, v28
	v_exp_f32_e32 v29, v29
	v_add_f32_e32 v4, 1.0, v4
	v_add_f32_e32 v19, 1.0, v19
	v_add_f32_e32 v28, 1.0, v28
	v_add_f32_e32 v29, 1.0, v29
	v_rcp_f32_e32 v33, v4
	v_rcp_f32_e32 v35, v19
	v_rcp_f32_e32 v37, v28
	v_rcp_f32_e32 v39, v29
	v_lshlrev_b32_e32 v24, 16, v20
	v_and_b32_e32 v20, 0xffff0000, v20
	v_pk_mul_f32 v[24:25], v[32:33], v[24:25]
	v_pk_mul_f32 v[20:21], v[34:35], v[20:21]
	v_pk_mul_f32 v[26:27], v[36:37], v[26:27]
	v_mov_b32_e32 v17, v3
	v_or_b32_e32 v16, 0xc0, v2
	v_pk_mul_f32 v[28:29], v[38:39], v[30:31]
	v_lshl_add_u64 v[16:17], v[12:13], 0, v[16:17]
	v_mov_b32_e32 v30, v5
	s_waitcnt vmcnt(23)
	v_mul_f32_e32 v4, v88, v24
	v_mul_f32_e32 v8, v89, v20
	v_mul_f32_e32 v9, v90, v26
	v_mul_f32_e32 v10, v91, v28
	v_mul_f32_e32 v8, v8, v21
	v_mul_f32_e32 v9, v9, v27
	v_mul_f32_e32 v4, v4, v25
	v_mul_f32_e32 v10, v10, v29
	v_cvt_pk_bf16_f32 v8, v4, v8
	v_cvt_pk_bf16_f32 v9, v9, v10
	global_store_dwordx2 v[16:17], v[8:9], off
	v_lshlrev_b32_e32 v26, 16, v23
	v_and_b32_e32 v28, 0xffff0000, v23
	v_lshlrev_b32_e32 v21, 16, v78
	v_and_b32_e32 v23, 0xffff0000, v78
	v_lshlrev_b32_e32 v27, 16, v79
	v_and_b32_e32 v29, 0xffff0000, v79
	v_mul_f32_e32 v4, 0xbfb8aa3b, v21
	v_mul_f32_e32 v6, 0xbfb8aa3b, v23
	v_mul_f32_e32 v7, 0xbfb8aa3b, v27
	v_mul_f32_e32 v19, 0xbfb8aa3b, v29
	v_exp_f32_e32 v4, v4
	v_exp_f32_e32 v6, v6
	v_exp_f32_e32 v7, v7
	v_exp_f32_e32 v19, v19
	v_add_f32_e32 v4, 1.0, v4
	v_add_f32_e32 v6, 1.0, v6
	v_add_f32_e32 v7, 1.0, v7
	v_add_f32_e32 v19, 1.0, v19
	v_rcp_f32_e32 v31, v4
	v_rcp_f32_e32 v33, v6
	v_rcp_f32_e32 v35, v7
	v_rcp_f32_e32 v37, v19
	v_lshlrev_b32_e32 v20, 16, v22
	v_and_b32_e32 v22, 0xffff0000, v22
	v_pk_mul_f32 v[6:7], v[30:31], v[20:21]
	v_pk_mul_f32 v[20:21], v[32:33], v[22:23]
	v_pk_mul_f32 v[22:23], v[34:35], v[26:27]
	v_mov_b32_e32 v17, v3
	v_or_b32_e32 v16, 0xe0, v2
	v_pk_mul_f32 v[26:27], v[36:37], v[28:29]
	v_lshl_add_u64 v[16:17], v[12:13], 0, v[16:17]
	s_waitcnt vmcnt(23)
	v_mul_f32_e32 v4, v92, v6
	v_mul_f32_e32 v6, v93, v20
	v_mul_f32_e32 v8, v94, v22
	v_mul_f32_e32 v9, v95, v26
	v_mul_f32_e32 v4, v4, v7
	v_mul_f32_e32 v6, v6, v21
	v_mul_f32_e32 v7, v8, v23
	v_mul_f32_e32 v8, v9, v27
	v_cvt_pk_bf16_f32 v6, v4, v6
	v_cvt_pk_bf16_f32 v7, v7, v8
	global_store_dwordx2 v[16:17], v[6:7], off
	ds_read2_b64 v[20:23], v109 offset0:32 offset1:36
	s_waitcnt vmcnt(23)
	v_lshlrev_b32_e32 v31, 16, v96
	v_lshlrev_b32_e32 v33, 16, v97
	v_and_b32_e32 v35, 0xffff0000, v97
	s_waitcnt lgkmcnt(0)
	v_lshlrev_b32_e32 v32, 16, v21
	v_and_b32_e32 v34, 0xffff0000, v21
	v_and_b32_e32 v21, 0xffff0000, v96
	v_mul_f32_e32 v4, 0xbfb8aa3b, v31
	v_mul_f32_e32 v19, 0xbfb8aa3b, v21
	v_mul_f32_e32 v24, 0xbfb8aa3b, v33
	v_mul_f32_e32 v25, 0xbfb8aa3b, v35
	v_exp_f32_e32 v4, v4
	v_exp_f32_e32 v19, v19
	v_exp_f32_e32 v24, v24
	v_exp_f32_e32 v25, v25
	v_add_f32_e32 v4, 1.0, v4
	v_add_f32_e32 v19, 1.0, v19
	v_add_f32_e32 v24, 1.0, v24
	v_add_f32_e32 v25, 1.0, v25
	v_rcp_f32_e32 v37, v4
	v_rcp_f32_e32 v39, v19
	v_rcp_f32_e32 v41, v24
	v_rcp_f32_e32 v43, v25
	v_lshlrev_b32_e32 v30, 16, v20
	v_and_b32_e32 v20, 0xffff0000, v20
	v_pk_mul_f32 v[24:25], v[36:37], v[30:31]
	v_pk_mul_f32 v[20:21], v[38:39], v[20:21]
	v_pk_mul_f32 v[30:31], v[40:41], v[32:33]
	v_mov_b32_e32 v17, v3
	v_or_b32_e32 v16, 0x100, v2
	v_pk_mul_f32 v[32:33], v[42:43], v[34:35]
	v_lshl_add_u64 v[16:17], v[12:13], 0, v[16:17]
	v_mov_b32_e32 v34, v5
	s_waitcnt vmcnt(22)
	v_mul_f32_e32 v4, v98, v24
	v_mul_f32_e32 v8, v99, v20
	v_mul_f32_e32 v9, v100, v30
	v_mul_f32_e32 v10, v101, v32
	v_mul_f32_e32 v8, v8, v21
	v_mul_f32_e32 v9, v9, v31
	v_mul_f32_e32 v4, v4, v25
	v_mul_f32_e32 v10, v10, v33
	v_cvt_pk_bf16_f32 v8, v4, v8
	v_cvt_pk_bf16_f32 v9, v9, v10
	global_store_dwordx2 v[16:17], v[8:9], off
	v_lshlrev_b32_e32 v24, 16, v23
	v_and_b32_e32 v30, 0xffff0000, v23
	s_waitcnt vmcnt(22)
	v_lshlrev_b32_e32 v21, 16, v102
	v_and_b32_e32 v23, 0xffff0000, v102
	v_lshlrev_b32_e32 v25, 16, v103
	v_and_b32_e32 v31, 0xffff0000, v103
	v_mul_f32_e32 v4, 0xbfb8aa3b, v21
	v_mul_f32_e32 v19, 0xbfb8aa3b, v23
	v_mul_f32_e32 v26, 0xbfb8aa3b, v25
	v_mul_f32_e32 v27, 0xbfb8aa3b, v31
	v_exp_f32_e32 v4, v4
	v_exp_f32_e32 v19, v19
	v_exp_f32_e32 v26, v26
	v_exp_f32_e32 v27, v27
	v_add_f32_e32 v4, 1.0, v4
	v_add_f32_e32 v19, 1.0, v19
	v_add_f32_e32 v26, 1.0, v26
	v_add_f32_e32 v27, 1.0, v27
	v_rcp_f32_e32 v33, v4
	v_rcp_f32_e32 v35, v19
	v_rcp_f32_e32 v37, v26
	v_rcp_f32_e32 v39, v27
	v_lshlrev_b32_e32 v20, 16, v22
	v_and_b32_e32 v22, 0xffff0000, v22
	v_mov_b32_e32 v32, v5
	v_pk_mul_f32 v[20:21], v[32:33], v[20:21]
	v_pk_mul_f32 v[22:23], v[34:35], v[22:23]
	v_pk_mul_f32 v[24:25], v[36:37], v[24:25]
	v_mov_b32_e32 v17, v3
	v_or_b32_e32 v16, 0x120, v2
	v_pk_mul_f32 v[26:27], v[38:39], v[30:31]
	v_lshl_add_u64 v[16:17], v[12:13], 0, v[16:17]
	s_waitcnt vmcnt(21)
	v_and_b32_e32 v31, 0xffff0000, v105
	s_waitcnt vmcnt(19)
	v_mul_f32_e32 v4, v116, v20
	v_mul_f32_e32 v8, v117, v22
	v_mul_f32_e32 v9, v118, v24
	v_mul_f32_e32 v10, v119, v26
	v_mul_f32_e32 v8, v8, v23
	v_mul_f32_e32 v9, v9, v25
	v_mul_f32_e32 v4, v4, v21
	v_mul_f32_e32 v10, v10, v27
	v_cvt_pk_bf16_f32 v8, v4, v8
	v_cvt_pk_bf16_f32 v9, v9, v10
	global_store_dwordx2 v[16:17], v[8:9], off
	ds_read2_b64 v[20:23], v109 offset0:40 offset1:44
	v_lshlrev_b32_e32 v25, 16, v104
	v_lshlrev_b32_e32 v27, 16, v105
	v_mul_f32_e32 v4, 0xbfb8aa3b, v25
	v_mul_f32_e32 v29, 0xbfb8aa3b, v31
	s_waitcnt lgkmcnt(0)
	v_lshlrev_b32_e32 v26, 16, v21
	v_and_b32_e32 v30, 0xffff0000, v21
	v_and_b32_e32 v21, 0xffff0000, v104
	v_mul_f32_e32 v19, 0xbfb8aa3b, v21
	v_mul_f32_e32 v28, 0xbfb8aa3b, v27
	v_exp_f32_e32 v4, v4
	v_exp_f32_e32 v19, v19
	v_exp_f32_e32 v28, v28
	v_exp_f32_e32 v29, v29
	v_add_f32_e32 v4, 1.0, v4
	v_add_f32_e32 v19, 1.0, v19
	v_add_f32_e32 v28, 1.0, v28
	v_add_f32_e32 v29, 1.0, v29
	v_rcp_f32_e32 v33, v4
	v_rcp_f32_e32 v35, v19
	v_rcp_f32_e32 v37, v28
	v_rcp_f32_e32 v39, v29
	v_lshlrev_b32_e32 v24, 16, v20
	v_and_b32_e32 v20, 0xffff0000, v20
	v_pk_mul_f32 v[24:25], v[32:33], v[24:25]
	v_pk_mul_f32 v[20:21], v[34:35], v[20:21]
	v_pk_mul_f32 v[26:27], v[36:37], v[26:27]
	v_mov_b32_e32 v17, v3
	v_or_b32_e32 v16, 0x140, v2
	v_pk_mul_f32 v[28:29], v[38:39], v[30:31]
	v_lshl_add_u64 v[16:17], v[12:13], 0, v[16:17]
	v_mov_b32_e32 v30, v5
	s_waitcnt vmcnt(19)
	v_mul_f32_e32 v4, v120, v24
	v_mul_f32_e32 v8, v121, v20
	v_mul_f32_e32 v9, v122, v26
	v_mul_f32_e32 v10, v123, v28
	v_mul_f32_e32 v8, v8, v21
	v_mul_f32_e32 v9, v9, v27
	v_mul_f32_e32 v4, v4, v25
	v_mul_f32_e32 v10, v10, v29
	v_cvt_pk_bf16_f32 v8, v4, v8
	v_cvt_pk_bf16_f32 v9, v9, v10
	global_store_dwordx2 v[16:17], v[8:9], off
	v_lshlrev_b32_e32 v26, 16, v23
	v_and_b32_e32 v28, 0xffff0000, v23
	v_lshlrev_b32_e32 v21, 16, v106
	v_and_b32_e32 v23, 0xffff0000, v106
	v_lshlrev_b32_e32 v27, 16, v107
	v_and_b32_e32 v29, 0xffff0000, v107
	v_mul_f32_e32 v4, 0xbfb8aa3b, v21
	v_mul_f32_e32 v6, 0xbfb8aa3b, v23
	v_mul_f32_e32 v7, 0xbfb8aa3b, v27
	v_mul_f32_e32 v19, 0xbfb8aa3b, v29
	v_exp_f32_e32 v4, v4
	v_exp_f32_e32 v6, v6
	v_exp_f32_e32 v7, v7
	v_exp_f32_e32 v19, v19
	v_add_f32_e32 v4, 1.0, v4
	v_add_f32_e32 v6, 1.0, v6
	v_add_f32_e32 v7, 1.0, v7
	v_add_f32_e32 v19, 1.0, v19
	v_rcp_f32_e32 v31, v4
	v_rcp_f32_e32 v33, v6
	v_rcp_f32_e32 v35, v7
	v_rcp_f32_e32 v37, v19
	v_lshlrev_b32_e32 v20, 16, v22
	v_and_b32_e32 v22, 0xffff0000, v22
	v_pk_mul_f32 v[6:7], v[30:31], v[20:21]
	v_pk_mul_f32 v[20:21], v[32:33], v[22:23]
	v_pk_mul_f32 v[22:23], v[34:35], v[26:27]
	v_mov_b32_e32 v17, v3
	v_or_b32_e32 v16, 0x160, v2
	v_pk_mul_f32 v[26:27], v[36:37], v[28:29]
	v_lshl_add_u64 v[16:17], v[12:13], 0, v[16:17]
	s_waitcnt vmcnt(19)
	v_mul_f32_e32 v4, v124, v6
	v_mul_f32_e32 v6, v125, v20
	v_mul_f32_e32 v8, v126, v22
	v_mul_f32_e32 v9, v127, v26
	v_mul_f32_e32 v4, v4, v7
	v_mul_f32_e32 v6, v6, v21
	v_mul_f32_e32 v7, v8, v23
	v_mul_f32_e32 v8, v9, v27
	v_cvt_pk_bf16_f32 v6, v4, v6
	v_cvt_pk_bf16_f32 v7, v7, v8
	global_store_dwordx2 v[16:17], v[6:7], off
	ds_read2_b64 v[20:23], v109 offset0:48 offset1:52
	v_mov_b32_e32 v17, v3
	v_or_b32_e32 v16, 0x180, v2
	v_lshl_add_u64 v[14:15], v[12:13], 0, v[16:17]
	s_waitcnt lgkmcnt(0)
	v_lshlrev_b32_e32 v30, 16, v21
	v_and_b32_e32 v32, 0xffff0000, v21
	s_waitcnt vmcnt(19)
	v_lshlrev_b32_e32 v17, 16, v132
	v_and_b32_e32 v21, 0xffff0000, v132
	v_lshlrev_b32_e32 v31, 16, v133
	v_and_b32_e32 v33, 0xffff0000, v133
	v_mul_f32_e32 v4, 0xbfb8aa3b, v17
	v_mul_f32_e32 v19, 0xbfb8aa3b, v21
	v_mul_f32_e32 v24, 0xbfb8aa3b, v31
	v_mul_f32_e32 v25, 0xbfb8aa3b, v33
	v_exp_f32_e32 v4, v4
	v_exp_f32_e32 v19, v19
	v_exp_f32_e32 v24, v24
	v_exp_f32_e32 v25, v25
	v_add_f32_e32 v4, 1.0, v4
	v_add_f32_e32 v19, 1.0, v19
	v_add_f32_e32 v24, 1.0, v24
	v_add_f32_e32 v25, 1.0, v25
	v_rcp_f32_e32 v35, v4
	v_rcp_f32_e32 v37, v19
	v_rcp_f32_e32 v39, v24
	v_rcp_f32_e32 v41, v25
	v_lshlrev_b32_e32 v16, 16, v20
	v_and_b32_e32 v20, 0xffff0000, v20
	v_pk_mul_f32 v[16:17], v[34:35], v[16:17]
	v_pk_mul_f32 v[20:21], v[36:37], v[20:21]
	v_pk_mul_f32 v[24:25], v[38:39], v[30:31]
	v_pk_mul_f32 v[30:31], v[40:41], v[32:33]
	v_mov_b32_e32 v32, v5
	s_waitcnt vmcnt(18)
	v_mul_f32_e32 v4, v134, v16
	v_mul_f32_e32 v8, v135, v20
	v_mul_f32_e32 v9, v136, v24
	v_mul_f32_e32 v10, v137, v30
	v_mul_f32_e32 v8, v8, v21
	v_mul_f32_e32 v9, v9, v25
	v_mul_f32_e32 v4, v4, v17
	v_mul_f32_e32 v10, v10, v31
	v_cvt_pk_bf16_f32 v8, v4, v8
	v_cvt_pk_bf16_f32 v9, v9, v10
	global_store_dwordx2 v[14:15], v[8:9], off
	v_lshlrev_b32_e32 v16, 16, v22
	v_and_b32_e32 v20, 0xffff0000, v22
	v_lshlrev_b32_e32 v22, 16, v23
	v_and_b32_e32 v24, 0xffff0000, v23
	s_waitcnt vmcnt(18)
	v_lshlrev_b32_e32 v17, 16, v138
	v_and_b32_e32 v21, 0xffff0000, v138
	v_lshlrev_b32_e32 v23, 16, v139
	v_and_b32_e32 v25, 0xffff0000, v139
	v_mul_f32_e32 v4, 0xbfb8aa3b, v17
	v_mul_f32_e32 v19, 0xbfb8aa3b, v21
	v_mul_f32_e32 v26, 0xbfb8aa3b, v23
	v_mul_f32_e32 v27, 0xbfb8aa3b, v25
	v_exp_f32_e32 v4, v4
	v_exp_f32_e32 v19, v19
	v_exp_f32_e32 v26, v26
	v_exp_f32_e32 v27, v27
	v_add_f32_e32 v4, 1.0, v4
	v_add_f32_e32 v19, 1.0, v19
	v_add_f32_e32 v26, 1.0, v26
	v_add_f32_e32 v27, 1.0, v27
	v_rcp_f32_e32 v31, v4
	v_rcp_f32_e32 v33, v19
	v_rcp_f32_e32 v35, v26
	v_rcp_f32_e32 v37, v27
	v_mov_b32_e32 v30, v5
	v_pk_mul_f32 v[16:17], v[30:31], v[16:17]
	v_pk_mul_f32 v[20:21], v[32:33], v[20:21]
	v_pk_mul_f32 v[22:23], v[34:35], v[22:23]
	v_mov_b32_e32 v15, v3
	v_or_b32_e32 v14, 0x1a0, v2
	v_pk_mul_f32 v[24:25], v[36:37], v[24:25]
	v_lshl_add_u64 v[14:15], v[12:13], 0, v[14:15]
	s_waitcnt vmcnt(17)
	v_and_b32_e32 v27, 0xffff0000, v141
	s_waitcnt vmcnt(15)
	v_mul_f32_e32 v4, v144, v16
	v_mul_f32_e32 v8, v145, v20
	v_mul_f32_e32 v9, v146, v22
	v_mul_f32_e32 v10, v147, v24
	v_mul_f32_e32 v8, v8, v21
	v_mul_f32_e32 v9, v9, v23
	v_mul_f32_e32 v4, v4, v17
	v_mul_f32_e32 v10, v10, v25
	v_cvt_pk_bf16_f32 v8, v4, v8
	v_cvt_pk_bf16_f32 v9, v9, v10
	global_store_dwordx2 v[14:15], v[8:9], off
	ds_read2_b64 v[14:17], v109 offset0:56 offset1:60
	v_lshlrev_b32_e32 v23, 16, v140
	v_lshlrev_b32_e32 v25, 16, v141
	v_mul_f32_e32 v4, 0xbfb8aa3b, v23
	v_mul_f32_e32 v29, 0xbfb8aa3b, v27
	s_waitcnt lgkmcnt(0)
	v_lshlrev_b32_e32 v24, 16, v15
	v_and_b32_e32 v26, 0xffff0000, v15
	v_and_b32_e32 v15, 0xffff0000, v140
	v_mul_f32_e32 v19, 0xbfb8aa3b, v15
	v_mul_f32_e32 v28, 0xbfb8aa3b, v25
	v_exp_f32_e32 v4, v4
	v_exp_f32_e32 v19, v19
	v_exp_f32_e32 v28, v28
	v_exp_f32_e32 v29, v29
	v_add_f32_e32 v4, 1.0, v4
	v_add_f32_e32 v19, 1.0, v19
	v_add_f32_e32 v28, 1.0, v28
	v_add_f32_e32 v29, 1.0, v29
	v_rcp_f32_e32 v31, v4
	v_rcp_f32_e32 v33, v19
	v_rcp_f32_e32 v35, v28
	v_rcp_f32_e32 v37, v29
	v_lshlrev_b32_e32 v22, 16, v14
	v_and_b32_e32 v14, 0xffff0000, v14
	v_pk_mul_f32 v[22:23], v[30:31], v[22:23]
	v_pk_mul_f32 v[14:15], v[32:33], v[14:15]
	v_pk_mul_f32 v[24:25], v[34:35], v[24:25]
	v_mov_b32_e32 v21, v3
	v_or_b32_e32 v20, 0x1c0, v2
	v_pk_mul_f32 v[26:27], v[36:37], v[26:27]
	v_lshl_add_u64 v[20:21], v[12:13], 0, v[20:21]
	v_or_b32_e32 v2, 0x1e0, v2
	v_mov_b32_e32 v28, v5
	v_lshlrev_b32_e32 v19, 16, v143
	v_lshl_add_u64 v[12:13], v[12:13], 0, v[2:3]
	v_mov_b32_e32 v30, v0
	s_waitcnt vmcnt(15)
	v_mul_f32_e32 v4, v148, v22
	v_mul_f32_e32 v8, v149, v14
	v_mul_f32_e32 v9, v150, v24
	v_mul_f32_e32 v10, v151, v26
	v_mul_f32_e32 v8, v8, v15
	v_mul_f32_e32 v9, v9, v25
	v_mul_f32_e32 v4, v4, v23
	v_mul_f32_e32 v10, v10, v27
	v_cvt_pk_bf16_f32 v8, v4, v8
	v_cvt_pk_bf16_f32 v9, v9, v10
	global_store_dwordx2 v[20:21], v[8:9], off
	v_lshlrev_b32_e32 v18, 16, v17
	v_and_b32_e32 v20, 0xffff0000, v17
	v_mov_b32_e32 v22, v5
	v_mov_b32_e32 v24, v5
	v_mov_b32_e32 v26, v5
	v_lshlrev_b32_e32 v5, 16, v142
	v_and_b32_e32 v17, 0xffff0000, v142
	v_and_b32_e32 v21, 0xffff0000, v143
	v_mul_f32_e32 v2, 0xbfb8aa3b, v5
	v_mul_f32_e32 v6, 0xbfb8aa3b, v17
	v_mul_f32_e32 v7, 0xbfb8aa3b, v19
	v_mul_f32_e32 v23, 0xbfb8aa3b, v21
	v_exp_f32_e32 v2, v2
	v_exp_f32_e32 v6, v6
	v_exp_f32_e32 v7, v7
	v_exp_f32_e32 v23, v23
	v_add_f32_e32 v2, 1.0, v2
	v_add_f32_e32 v6, 1.0, v6
	v_add_f32_e32 v7, 1.0, v7
	v_add_f32_e32 v29, 1.0, v23
	v_rcp_f32_e32 v23, v2
	v_rcp_f32_e32 v25, v6
	v_rcp_f32_e32 v27, v7
	v_rcp_f32_e32 v29, v29
	v_lshlrev_b32_e32 v4, 16, v16
	v_and_b32_e32 v16, 0xffff0000, v16
	v_pk_mul_f32 v[4:5], v[22:23], v[4:5]
	v_pk_mul_f32 v[6:7], v[24:25], v[16:17]
	v_pk_mul_f32 v[16:17], v[26:27], v[18:19]
	v_pk_mul_f32 v[18:19], v[28:29], v[20:21]
	v_mov_b64_e32 v[14:15], s[88:89]
	s_waitcnt vmcnt(15)
	v_mul_f32_e32 v2, v152, v4
	v_mul_f32_e32 v4, v153, v6
	v_mul_f32_e32 v6, v154, v16
	v_mul_f32_e32 v8, v155, v18
	v_mul_f32_e32 v2, v2, v5
	v_mul_f32_e32 v4, v4, v7
	v_mul_f32_e32 v5, v6, v17
	v_mul_f32_e32 v6, v8, v19
	v_cvt_pk_bf16_f32 v4, v2, v4
	v_cvt_pk_bf16_f32 v5, v5, v6
	global_store_dwordx2 v[12:13], v[4:5], off
	s_nop 0
	v_and_b32_e32 v52, 15, v30
	v_ashrrev_i32_e32 v2, 6, v30
	v_or_b32_e32 v5, s20, v52
	v_ashrrev_i32_e32 v46, 1, v30
	v_lshl_add_u32 v116, v2, 4, v5
	v_lshl_add_u32 v4, s0, 8, v46
	v_mad_i64_i32 v[118:119], s[0:1], v116, s92, v[14:15]
	v_ashrrev_i32_e32 v5, 31, v4
	v_readlane_b32 s0, v244, 50
	v_and_b32_e32 v50, 1, v30
	v_lshlrev_b64 v[4:5], 10, v[4:5]
	v_readlane_b32 s1, v244, 51
	v_bfe_u32 v47, v30, 4, 2
	v_lshlrev_b32_e32 v44, 6, v50
	v_lshl_add_u64 v[4:5], s[0:1], 0, v[4:5]
	v_lshlrev_b32_e32 v114, 4, v47
	v_lshl_add_u64 v[20:21], v[4:5], 0, v[44:45]
	v_lshl_add_u64 v[120:121], v[118:119], 0, v[114:115]
	global_load_dwordx4 v[4:7], v[20:21], off offset:48
	global_load_dwordx4 v[12:15], v[20:21], off offset:32
	global_load_dwordx4 v[16:19], v[20:21], off offset:16
	global_load_dwordx4 v[8:11], v[20:21], off
	global_load_dwordx4 v[28:31], v[20:21], off offset:512
	global_load_dwordx4 v[32:35], v[20:21], off offset:528
	global_load_dwordx4 v[36:39], v[20:21], off offset:544
	global_load_dwordx4 v[40:43], v[20:21], off offset:560
	s_nop 0
	global_load_dwordx4 v[20:23], v[120:121], off offset:3584
	global_load_dwordx4 v[24:27], v[120:121], off offset:3648
	v_readlane_b32 s0, v243, 0
	v_mul_lo_u32 v45, v46, s97
	s_and_b32 s0, s0, 7
	v_add_u32_e32 v48, 0, v45
	s_lshl_b32 s2, s0, 18
	v_add_u32_e32 v132, v48, v44
	v_mad_u64_u32 v[48:49], s[0:1], v46, s98, v[48:49]
	v_mul_u32_u24_e32 v45, 0x4200, v50
	v_lshlrev_b32_e32 v50, 7, v50
	v_mul_lo_u32 v131, v2, s93
	v_lshlrev_b32_e32 v2, 3, v47
	v_lshl_add_u64 v[122:123], s[10:11], 0, v[50:51]
	v_lshlrev_b32_e32 v50, 5, v47
	v_or_b32_e32 v47, 16, v52
	s_movk_i32 s0, 0x210
	v_lshl_add_u64 v[124:125], s[8:9], 0, v[50:51]
	global_load_dwordx4 v[224:227], v[124:125], off
	global_load_dwordx4 v[228:231], v[124:125], off offset:128
	global_load_dwordx4 v[232:235], v[124:125], off offset:16
	global_load_dwordx4 v[236:239], v[124:125], off offset:144
	v_mul_u32_u24_e32 v51, 0x210, v47
	v_mad_u32_u24 v47, v52, s0, v131
	v_add3_u32 v134, v47, v2, s96
	v_ashrrev_i32_e32 v47, 31, v46
	v_lshlrev_b64 v[46:47], 10, v[46:47]
	v_add_u32_e32 v49, 0, v114
	s_mov_b32 s1, s3
	v_lshl_add_u64 v[46:47], s[2:3], 0, v[46:47]
	v_mov_b32_e32 v133, v49
	v_mul_u32_u24_e32 v50, 0x90, v52
	v_writelane_b32 v244, s0, 62
	v_or_b32_e32 v46, v46, v44
	v_mul_u32_u24_e32 v115, 0x210, v52
	v_ashrrev_i32_e32 v117, 31, v116
	v_writelane_b32 v244, s1, 63
	v_lshl_add_u64 v[126:127], s[6:7], 0, v[46:47]
	s_mov_b64 s[0:1], 64
	v_and_b32_e32 v241, 24, v48
	v_and_b32_e32 v242, 32, v48
	v_and_b32_e32 v48, 0xffffffc7, v48
	v_lshlrev_b32_e32 v241, 1, v241
	v_lshrrev_b32_e32 v242, 2, v242
	v_or3_b32 v48, v48, v241, v242
	v_add_u32_e32 v135, v48, v45
	v_add_u32_e32 v136, v49, v50
	v_add_u32_e32 v137, v133, v51
	v_add_u32_e32 v240, v133, v115
	v_add_u32_e32 v240, 0x9000, v240
	v_add_u32_e32 v241, 0x9000, v137
	v_add_u32_e32 v242, 0xb000, v137
	v_add_u32_e32 v245, 0xd000, v137
	s_branch .LBB0_210
.LBB0_209:
	ds_read_b128 v[172:175], v136
	ds_read_b128 v[176:179], v136 offset:64
	ds_read_b128 v[196:199], v136 offset:2304
	ds_read_b128 v[200:203], v136 offset:2368
	ds_read_b128 v[204:207], v136 offset:4672
	ds_read_b128 v[208:211], v136 offset:4608
	ds_read_b128 v[212:215], v136 offset:6912
	ds_read_b128 v[216:219], v136 offset:6976
	s_add_u32 s0, s0, 64
	s_addc_u32 s1, s1, 0
	s_waitcnt lgkmcnt(7)
	v_mfma_f32_16x16x32_bf16 v[48:51], v[172:175], v[104:107], 0
	ds_read_b128 v[220:223], v136 offset:9216
	s_add_u32 s4, s4, 0x80
	s_addc_u32 s5, s5, 0
	s_cmpk_lg_i32 s4, 0x200
	s_waitcnt lgkmcnt(6)
	v_mfma_f32_16x16x32_bf16 v[56:59], v[196:199], v[104:107], 0
	ds_read_b128 v[172:175], v136 offset:11520
	v_mfma_f32_16x16x32_bf16 v[108:111], v[176:179], v[44:47], v[48:51]
	ds_read_b128 v[196:199], v136 offset:9280
	s_nop 1
	s_waitcnt lgkmcnt(7)
	v_mfma_f32_16x16x32_bf16 v[100:103], v[200:203], v[44:47], v[56:59]
	ds_read_b128 v[176:179], v136 offset:11584
	s_nop 2
	s_waitcnt lgkmcnt(6)
	v_mfma_f32_16x16x32_bf16 v[48:51], v[208:211], v[104:107], 0
	ds_read_b128 v[200:203], v136 offset:13888
	v_mfma_f32_16x16x32_bf16 v[96:99], v[204:207], v[44:47], v[48:51]
	ds_read_b128 v[208:211], v136 offset:13824
	s_nop 6
	s_waitcnt lgkmcnt(7)
	v_mfma_f32_16x16x32_bf16 v[52:55], v[212:215], v[104:107], 0
	ds_read_b128 v[204:207], v136 offset:16128
	s_waitcnt lgkmcnt(7)
	v_mfma_f32_16x16x32_bf16 v[92:95], v[216:219], v[44:47], v[52:55]
	ds_read_b128 v[212:215], v136 offset:16192
	s_waitcnt lgkmcnt(7)
	v_mfma_f32_16x16x32_bf16 v[52:55], v[220:223], v[104:107], 0
	ds_read_b128 v[216:219], v136 offset:18432
	s_waitcnt lgkmcnt(6)
	v_mfma_f32_16x16x32_bf16 v[88:91], v[196:199], v[44:47], v[52:55]
	ds_read_b128 v[220:223], v136 offset:18496
	s_nop 0
	v_mfma_f32_16x16x32_bf16 v[52:55], v[172:175], v[104:107], 0
	ds_read_b128 v[196:199], v136 offset:20736
	s_waitcnt lgkmcnt(7)
	v_mfma_f32_16x16x32_bf16 v[84:87], v[176:179], v[44:47], v[52:55]
	ds_read_b128 v[172:175], v136 offset:20800
	s_waitcnt lgkmcnt(6)
	v_mfma_f32_16x16x32_bf16 v[52:55], v[208:211], v[104:107], 0
	ds_read_b128 v[176:179], v136 offset:23040
	v_mfma_f32_16x16x32_bf16 v[80:83], v[200:203], v[44:47], v[52:55]
	ds_read_b128 v[208:211], v136 offset:23104
	s_waitcnt lgkmcnt(7)
	s_nop 0
	v_mfma_f32_16x16x32_bf16 v[52:55], v[204:207], v[104:107], 0
	ds_read_b128 v[200:203], v136 offset:25344
	s_waitcnt lgkmcnt(7)
	v_mfma_f32_16x16x32_bf16 v[76:79], v[212:215], v[44:47], v[52:55]
	ds_read_b128 v[204:207], v136 offset:25408
	s_waitcnt lgkmcnt(7)
	v_mfma_f32_16x16x32_bf16 v[52:55], v[216:219], v[104:107], 0
	ds_read_b128 v[212:215], v136 offset:27648
	s_waitcnt lgkmcnt(7)
	v_mfma_f32_16x16x32_bf16 v[68:71], v[220:223], v[44:47], v[52:55]
	ds_read_b128 v[216:219], v136 offset:27712
	s_waitcnt lgkmcnt(7)
	v_mfma_f32_16x16x32_bf16 v[52:55], v[196:199], v[104:107], 0
	ds_read_b128 v[220:223], v136 offset:29952
	s_waitcnt lgkmcnt(6)
	v_mfma_f32_16x16x32_bf16 v[56:59], v[176:179], v[104:107], 0
	ds_read_b128 v[196:199], v136 offset:32256
	s_waitcnt lgkmcnt(6)
	v_mfma_f32_16x16x32_bf16 v[72:75], v[208:211], v[44:47], v[56:59]
	ds_read_b128 v[176:179], v136 offset:32320
	v_mfma_f32_16x16x32_bf16 v[64:67], v[172:175], v[44:47], v[52:55]
	ds_read_b128 v[208:211], v136 offset:30016
	s_nop 4
	v_max3_f32 v56, v108, s16, v109
	v_max3_f32 v56, v56, v110, v111
	v_max3_f32 v60, v56, v100, v101
	s_waitcnt lgkmcnt(7)
	v_mfma_f32_16x16x32_bf16 v[56:59], v[200:203], v[104:107], 0
	ds_read_b128 v[172:175], v136 offset:34560
	v_max3_f32 v60, v60, v102, v103
	v_max3_f32 v60, v60, v96, v97
	v_max3_f32 v138, v60, v98, v99
	s_waitcnt lgkmcnt(7)
	v_mfma_f32_16x16x32_bf16 v[60:63], v[204:207], v[44:47], v[56:59]
	ds_read_b128 v[200:203], v136 offset:34624
	v_max3_f32 v56, v138, v92, v93
	v_max3_f32 v56, v56, v94, v95
	v_max3_f32 v56, v56, v88, v89
	s_waitcnt lgkmcnt(7)
	v_mfma_f32_16x16x32_bf16 v[48:51], v[212:215], v[104:107], 0
	ds_read_b128 v[204:207], v240
	v_max3_f32 v56, v56, v90, v91
	v_max3_f32 v56, v56, v84, v85
	v_max3_f32 v138, v56, v86, v87
	s_waitcnt lgkmcnt(7)
	v_mfma_f32_16x16x32_bf16 v[56:59], v[216:219], v[44:47], v[48:51]
	ds_read_b128 v[212:215], v241
	s_nop 2
	v_max3_f32 v48, v138, v80, v81
	v_max3_f32 v48, v48, v82, v83
	v_max3_f32 v52, v48, v76, v77
	s_waitcnt lgkmcnt(7)
	v_mfma_f32_16x16x32_bf16 v[48:51], v[220:223], v[104:107], 0
	ds_read_b128 v[216:219], v242 offset:256
	v_max3_f32 v52, v52, v78, v79
	v_max3_f32 v52, v52, v68, v69
	v_max3_f32 v138, v52, v70, v71
	s_waitcnt lgkmcnt(5)
	v_mfma_f32_16x16x32_bf16 v[52:55], v[208:211], v[44:47], v[48:51]
	ds_read_b128 v[220:223], v245 offset:512
	s_nop 2
	v_max3_f32 v48, v138, v64, v65
	v_max3_f32 v48, v48, v66, v67
	v_max3_f32 v138, v48, v72, v73
	s_nop 0
	v_mfma_f32_16x16x32_bf16 v[48:51], v[196:199], v[104:107], 0
	ds_read_b128 v[208:211], v240 offset:64
	v_max3_f32 v138, v138, v74, v75
	v_max3_f32 v138, v138, v60, v61
	v_max3_f32 v138, v138, v62, v63
	s_waitcnt lgkmcnt(6)
	v_mfma_f32_16x16x32_bf16 v[104:107], v[172:175], v[104:107], 0
	ds_read_b128 v[196:199], v241 offset:64
	v_max3_f32 v138, v138, v56, v57
	v_max3_f32 v138, v138, v58, v59
	v_max3_f32 v138, v138, v52, v53
	v_mfma_f32_16x16x32_bf16 v[48:51], v[176:179], v[44:47], v[48:51]
	ds_read_b128 v[172:175], v242 offset:320
	v_max3_f32 v138, v138, v54, v55
	s_waitcnt lgkmcnt(7)
	v_mfma_f32_16x16x32_bf16 v[44:47], v[200:203], v[44:47], v[104:107]
	ds_read_b128 v[176:179], v245 offset:576
	s_nop 4
	v_max3_f32 v138, v138, v48, v49
	v_max3_f32 v138, v138, v50, v51
	s_nop 0
	v_max3_f32 v104, v138, v44, v45
	v_max3_f32 v104, v104, v46, v47
	v_mov_b32_e32 v105, v104
	s_nop 1
	v_permlane16_swap_b32 v105, v104
	s_nop 0
	v_max_f32_e32 v105, v105, v105
	v_max_f32_e32 v104, v104, v105
	v_mov_b32_e32 v105, v104
	s_nop 1
	v_permlane32_swap_b32 v105, v104
	s_nop 0
	v_max_f32_e32 v105, v105, v105
	v_max_f32_e32 v104, v104, v105
	v_sub_f32_e32 v105, v108, v104
	v_exp_f32_e32 v106, v105
	v_sub_f32_e32 v105, v109, v104
	v_exp_f32_e32 v107, v105
	v_sub_f32_e32 v105, v110, v104
	v_exp_f32_e32 v108, v105
	v_sub_f32_e32 v105, v111, v104
	v_exp_f32_e32 v110, v105
	v_sub_f32_e32 v100, v100, v104
	v_add_f32_e32 v105, 0, v106
	v_exp_f32_e32 v109, v100
	v_sub_f32_e32 v100, v101, v104
	v_add_f32_e32 v105, v107, v105
	v_exp_f32_e32 v111, v100
	v_sub_f32_e32 v100, v102, v104
	v_add_f32_e32 v105, v108, v105
	v_exp_f32_e32 v138, v100
	v_sub_f32_e32 v100, v103, v104
	v_add_f32_e32 v105, v110, v105
	v_exp_f32_e32 v139, v100
	v_add_f32_e32 v100, v109, v105
	v_add_f32_e32 v100, v111, v100
	v_add_f32_e32 v100, v138, v100
	v_sub_f32_e32 v96, v96, v104
	v_add_f32_e32 v102, v139, v100
	v_exp_f32_e32 v100, v96
	v_sub_f32_e32 v96, v97, v104
	v_exp_f32_e32 v101, v96
	v_sub_f32_e32 v96, v98, v104
	v_exp_f32_e32 v97, v96
	v_sub_f32_e32 v96, v99, v104
	v_exp_f32_e32 v98, v96
	v_sub_f32_e32 v92, v92, v104
	v_add_f32_e32 v96, v100, v102
	v_exp_f32_e32 v99, v92
	v_sub_f32_e32 v92, v93, v104
	v_add_f32_e32 v96, v101, v96
	v_exp_f32_e32 v102, v92
	v_sub_f32_e32 v92, v94, v104
	v_add_f32_e32 v96, v97, v96
	v_exp_f32_e32 v103, v92
	v_sub_f32_e32 v92, v95, v104
	v_add_f32_e32 v96, v98, v96
	v_exp_f32_e32 v105, v92
	v_add_f32_e32 v92, v99, v96
	v_add_f32_e32 v92, v102, v92
	v_add_f32_e32 v92, v103, v92
	v_sub_f32_e32 v88, v88, v104
	v_add_f32_e32 v94, v105, v92
	v_exp_f32_e32 v92, v88
	v_sub_f32_e32 v88, v89, v104
	v_exp_f32_e32 v93, v88
	v_sub_f32_e32 v88, v90, v104
	v_exp_f32_e32 v89, v88
	v_sub_f32_e32 v88, v91, v104
	v_exp_f32_e32 v90, v88
	v_sub_f32_e32 v84, v84, v104
	v_add_f32_e32 v88, v92, v94
	v_exp_f32_e32 v91, v84
	v_sub_f32_e32 v84, v85, v104
	v_add_f32_e32 v88, v93, v88
	v_exp_f32_e32 v94, v84
	v_sub_f32_e32 v84, v86, v104
	v_add_f32_e32 v88, v89, v88
	v_exp_f32_e32 v95, v84
	v_sub_f32_e32 v84, v87, v104
	v_add_f32_e32 v88, v90, v88
	v_exp_f32_e32 v96, v84
	v_add_f32_e32 v84, v91, v88
	v_add_f32_e32 v84, v94, v84
	v_add_f32_e32 v84, v95, v84
	v_sub_f32_e32 v80, v80, v104
	v_add_f32_e32 v86, v96, v84
	v_exp_f32_e32 v84, v80
	v_sub_f32_e32 v80, v81, v104
	v_exp_f32_e32 v85, v80
	v_sub_f32_e32 v80, v82, v104
	v_exp_f32_e32 v81, v80
	v_sub_f32_e32 v80, v83, v104
	v_exp_f32_e32 v82, v80
	v_sub_f32_e32 v76, v76, v104
	v_add_f32_e32 v80, v84, v86
	v_exp_f32_e32 v83, v76
	v_sub_f32_e32 v76, v77, v104
	v_add_f32_e32 v80, v85, v80
	v_exp_f32_e32 v86, v76
	v_sub_f32_e32 v76, v78, v104
	v_add_f32_e32 v80, v81, v80
	v_exp_f32_e32 v87, v76
	v_sub_f32_e32 v76, v79, v104
	v_add_f32_e32 v80, v82, v80
	v_exp_f32_e32 v88, v76
	v_add_f32_e32 v76, v83, v80
	v_add_f32_e32 v76, v86, v76
	v_add_f32_e32 v76, v87, v76
	v_sub_f32_e32 v68, v68, v104
	v_add_f32_e32 v78, v88, v76
	v_exp_f32_e32 v76, v68
	v_sub_f32_e32 v68, v69, v104
	v_exp_f32_e32 v77, v68
	v_sub_f32_e32 v68, v70, v104
	v_exp_f32_e32 v68, v68
	v_sub_f32_e32 v69, v71, v104
	v_exp_f32_e32 v69, v69
	v_sub_f32_e32 v64, v64, v104
	v_add_f32_e32 v70, v76, v78
	v_exp_f32_e32 v71, v64
	v_sub_f32_e32 v64, v65, v104
	v_add_f32_e32 v70, v77, v70
	v_exp_f32_e32 v78, v64
	v_sub_f32_e32 v64, v66, v104
	v_add_f32_e32 v70, v68, v70
	v_exp_f32_e32 v79, v64
	v_sub_f32_e32 v64, v67, v104
	v_add_f32_e32 v70, v69, v70
	v_exp_f32_e32 v80, v64
	v_add_f32_e32 v64, v71, v70
	v_add_f32_e32 v64, v78, v64
	v_add_f32_e32 v64, v79, v64
	v_add_f32_e32 v70, v80, v64
	v_sub_f32_e32 v64, v72, v104
	v_exp_f32_e32 v65, v64
	v_sub_f32_e32 v64, v73, v104
	v_exp_f32_e32 v67, v64
	v_sub_f32_e32 v64, v74, v104
	v_exp_f32_e32 v64, v64
	v_sub_f32_e32 v66, v75, v104
	v_exp_f32_e32 v66, v66
	v_sub_f32_e32 v60, v60, v104
	v_add_f32_e32 v70, v65, v70
	v_exp_f32_e32 v60, v60
	v_sub_f32_e32 v61, v61, v104
	v_add_f32_e32 v70, v67, v70
	v_exp_f32_e32 v61, v61
	v_sub_f32_e32 v62, v62, v104
	v_add_f32_e32 v70, v64, v70
	v_exp_f32_e32 v62, v62
	v_sub_f32_e32 v63, v63, v104
	v_add_f32_e32 v70, v66, v70
	v_exp_f32_e32 v63, v63
	v_add_f32_e32 v70, v60, v70
	v_add_f32_e32 v70, v61, v70
	v_add_f32_e32 v70, v62, v70
	v_add_f32_e32 v75, v63, v70
	v_sub_f32_e32 v56, v56, v104
	v_add_u32_e32 v70, v133, v115
	v_add_u32_e32 v73, 0x9000, v70
	v_add_u32_e32 v72, 0x9000, v137
	v_add_u32_e32 v70, 0xb000, v137
	v_exp_f32_e32 v74, v56
	v_add_u32_e32 v56, 0xd000, v137
	v_cvt_pk_bf16_f32 v106, v106, v107
	v_cvt_pk_bf16_f32 v107, v108, v110
	v_cvt_pk_bf16_f32 v108, v109, v111
	v_cvt_pk_bf16_f32 v109, v138, v139
	s_waitcnt lgkmcnt(7)
	s_nop 0
	v_mfma_f32_16x16x32_bf16 v[138:141], v[204:207], v[106:109], 0
	ds_read_b128 v[200:203], v240 offset:128
	v_cvt_pk_bf16_f32 v100, v100, v101
	v_cvt_pk_bf16_f32 v101, v97, v98
	v_cvt_pk_bf16_f32 v102, v99, v102
	s_waitcnt lgkmcnt(7)
	v_mfma_f32_16x16x32_bf16 v[142:145], v[212:215], v[106:109], 0
	ds_read_b128 v[204:207], v242 offset:384
	v_cvt_pk_bf16_f32 v103, v103, v105
	v_cvt_pk_bf16_f32 v92, v92, v93
	s_waitcnt lgkmcnt(7)
	v_mfma_f32_16x16x32_bf16 v[146:149], v[216:219], v[106:109], 0
	ds_read_b128 v[212:215], v241 offset:128
	v_cvt_pk_bf16_f32 v93, v89, v90
	v_cvt_pk_bf16_f32 v94, v91, v94
	v_cvt_pk_bf16_f32 v95, v95, v96
	s_waitcnt lgkmcnt(7)
	v_mfma_f32_16x16x32_bf16 v[106:109], v[220:223], v[106:109], 0
	ds_read_b128 v[216:219], v245 offset:640
	v_cvt_pk_bf16_f32 v84, v84, v85
	v_cvt_pk_bf16_f32 v85, v81, v82
	s_waitcnt lgkmcnt(7)
	v_mfma_f32_16x16x32_bf16 v[138:141], v[208:211], v[100:103], v[138:141]
	ds_read_b128 v[220:223], v240 offset:192
	v_cvt_pk_bf16_f32 v86, v83, v86
	v_cvt_pk_bf16_f32 v87, v87, v88
	s_waitcnt lgkmcnt(7)
	v_mfma_f32_16x16x32_bf16 v[142:145], v[196:199], v[100:103], v[142:145]
	ds_read_b128 v[208:211], v242 offset:448
	v_sub_f32_e32 v57, v57, v104
	v_cvt_pk_bf16_f32 v76, v76, v77
	s_waitcnt lgkmcnt(7)
	v_mfma_f32_16x16x32_bf16 v[146:149], v[172:175], v[100:103], v[146:149]
	ds_read_b128 v[196:199], v241 offset:192
	v_cvt_pk_bf16_f32 v77, v68, v69
	v_cvt_pk_bf16_f32 v78, v71, v78
	v_cvt_pk_bf16_f32 v79, v79, v80
	s_waitcnt lgkmcnt(7)
	v_mfma_f32_16x16x32_bf16 v[98:101], v[176:179], v[100:103], v[106:109]
	ds_read_b128 v[172:175], v245 offset:704
	v_exp_f32_e32 v57, v57
	v_sub_f32_e32 v58, v58, v104
	s_waitcnt lgkmcnt(7)
	v_mfma_f32_16x16x32_bf16 v[138:141], v[200:203], v[92:95], v[138:141]
	ds_read_b128 v[176:179], v240 offset:256
	v_exp_f32_e32 v58, v58
	v_sub_f32_e32 v59, v59, v104
	s_waitcnt lgkmcnt(6)
	v_mfma_f32_16x16x32_bf16 v[106:109], v[212:215], v[92:95], v[142:145]
	ds_read_b128 v[200:203], v242 offset:512
	v_exp_f32_e32 v59, v59
	v_sub_f32_e32 v52, v52, v104
	v_add_f32_e32 v75, v74, v75
	v_mfma_f32_16x16x32_bf16 v[142:145], v[204:207], v[92:95], v[146:149]
	ds_read_b128 v[212:215], v241 offset:256
	v_exp_f32_e32 v52, v52
	v_sub_f32_e32 v53, v53, v104
	v_add_f32_e32 v75, v57, v75
	s_waitcnt lgkmcnt(7)
	v_mfma_f32_16x16x32_bf16 v[90:93], v[216:219], v[92:95], v[98:101]
	ds_read_b128 v[204:207], v245 offset:768
	v_exp_f32_e32 v53, v53
	v_sub_f32_e32 v54, v54, v104
	s_waitcnt lgkmcnt(7)
	v_mfma_f32_16x16x32_bf16 v[138:141], v[220:223], v[84:87], v[138:141]
	ds_read_b128 v[216:219], v241 offset:320
	v_add_f32_e32 v75, v58, v75
	v_exp_f32_e32 v54, v54
	s_waitcnt lgkmcnt(6)
	v_mfma_f32_16x16x32_bf16 v[94:97], v[196:199], v[84:87], v[106:109]
	ds_read_b128 v[220:223], v245 offset:832
	v_sub_f32_e32 v55, v55, v104
	v_add_f32_e32 v75, v59, v75
	v_exp_f32_e32 v55, v55
	v_mfma_f32_16x16x32_bf16 v[98:101], v[208:211], v[84:87], v[142:145]
	ds_read_b128 v[196:199], v242 offset:576
	v_sub_f32_e32 v48, v48, v104
	v_add_f32_e32 v75, v52, v75
	v_exp_f32_e32 v102, v48
	s_waitcnt lgkmcnt(7)
	v_mfma_f32_16x16x32_bf16 v[82:85], v[172:175], v[84:87], v[90:93]
	ds_read_b128 v[208:211], v240 offset:320
	v_sub_f32_e32 v48, v49, v104
	v_add_f32_e32 v75, v53, v75
	s_waitcnt lgkmcnt(7)
	v_mfma_f32_16x16x32_bf16 v[106:109], v[176:179], v[76:79], v[138:141]
	ds_read_b128 v[172:175], v240 offset:384
	v_exp_f32_e32 v103, v48
	v_sub_f32_e32 v48, v50, v104
	v_add_f32_e32 v75, v54, v75
	s_waitcnt lgkmcnt(6)
	v_mfma_f32_16x16x32_bf16 v[86:89], v[212:215], v[76:79], v[94:97]
	ds_read_b128 v[176:179], v242 offset:640
	v_exp_f32_e32 v68, v48
	v_add_f32_e32 v75, v55, v75
	v_cvt_pk_bf16_f32 v80, v65, v67
	v_mfma_f32_16x16x32_bf16 v[90:93], v[200:203], v[76:79], v[98:101]
	ds_read_b128 v[212:215], v241 offset:384
	v_cvt_pk_bf16_f32 v81, v64, v66
	s_waitcnt lgkmcnt(7)
	v_mfma_f32_16x16x32_bf16 v[76:79], v[204:207], v[76:79], v[82:85]
	ds_read_b128 v[200:203], v245 offset:896
	v_cvt_pk_bf16_f32 v82, v60, v61
	v_cvt_pk_bf16_f32 v83, v62, v63
	v_add_f32_e32 v48, v102, v75
	v_add_f32_e32 v48, v103, v48
	v_add_f32_e32 v69, v68, v48
	v_sub_f32_e32 v71, v51, v104
	s_waitcnt lgkmcnt(7)
	v_mfma_f32_16x16x32_bf16 v[84:87], v[216:219], v[80:83], v[86:89]
	ds_read_b128 v[204:207], v240 offset:448
	v_exp_f32_e32 v71, v71
	v_sub_f32_e32 v44, v44, v104
	v_exp_f32_e32 v94, v44
	s_waitcnt lgkmcnt(6)
	v_mfma_f32_16x16x32_bf16 v[60:63], v[196:199], v[80:83], v[90:93]
	ds_read_b128 v[216:219], v242 offset:704
	v_sub_f32_e32 v44, v45, v104
	v_exp_f32_e32 v95, v44
	v_sub_f32_e32 v45, v46, v104
	v_mfma_f32_16x16x32_bf16 v[64:67], v[220:223], v[80:83], v[76:79]
	ds_read_b128 v[196:199], v241 offset:448
	v_cvt_pk_bf16_f32 v76, v52, v53
	v_cvt_pk_bf16_f32 v77, v54, v55
	s_waitcnt lgkmcnt(7)
	v_mfma_f32_16x16x32_bf16 v[48:51], v[208:211], v[80:83], v[106:109]
	ds_read_b128 v[220:223], v245 offset:960
	v_add_f32_e32 v69, v71, v69
	v_cvt_pk_bf16_f32 v74, v74, v57
	v_exp_f32_e32 v57, v45
	v_sub_f32_e32 v45, v47, v104
	v_add_f32_e32 v44, v94, v69
	v_exp_f32_e32 v69, v45
	v_add_f32_e32 v44, v95, v44
	v_cvt_pk_bf16_f32 v75, v58, v59
	s_nop 0
	v_add_f32_e32 v58, v57, v44
	s_waitcnt lgkmcnt(7)
	v_mfma_f32_16x16x32_bf16 v[48:51], v[172:175], v[74:77], v[48:51]
	s_waitcnt lgkmcnt(6)
	v_mfma_f32_16x16x32_bf16 v[44:47], v[176:179], v[74:77], v[60:63]
	v_add_f32_e32 v73, v69, v58
	ds_bpermute_b32 v82, v128, v73
	v_cvt_pk_bf16_f32 v69, v57, v69
	s_waitcnt lgkmcnt(6)
	v_mfma_f32_16x16x32_bf16 v[78:81], v[212:215], v[74:77], v[84:87]
	s_waitcnt lgkmcnt(0)
	v_add_f32_e32 v57, v73, v82
	v_mfma_f32_16x16x32_bf16 v[58:61], v[200:203], v[74:77], v[64:67]
	ds_bpermute_b32 v74, v113, v57
	v_cvt_pk_bf16_f32 v66, v102, v103
	v_cvt_pk_bf16_f32 v67, v68, v71
	v_cvt_pk_bf16_f32 v68, v94, v95
	s_nop 0
	v_mfma_f32_16x16x32_bf16 v[48:51], v[204:207], v[66:69], v[48:51]
	s_waitcnt lgkmcnt(0)
	v_add_f32_e32 v56, v57, v74
	v_rcp_f32_e32 v56, v56
	v_mfma_f32_16x16x32_bf16 v[62:65], v[196:199], v[66:69], v[78:81]
	s_nop 3
	v_mul_f32_e64 v50, v56, v50
	v_mul_f32_e64 v51, v56, v51
	v_pk_mul_f32 v[48:49], v[56:57], v[48:49] op_sel_hi:[0,1]
	v_mfma_f32_16x16x32_bf16 v[44:47], v[216:219], v[66:69], v[44:47]
	v_mfma_f32_16x16x32_bf16 v[52:55], v[220:223], v[66:69], v[58:61]
	s_nop 2
	v_mul_f32_e64 v58, v50, v50
	v_mul_f32_e64 v59, v51, v51
	v_pk_mul_f32 v[60:61], v[48:49], v[48:49]
	v_cvt_pk_bf16_f32 v48, v48, v49
	v_cvt_pk_bf16_f32 v49, v50, v51
	s_nop 0
	v_pk_mov_b32 v[66:67], v[60:61], v[58:59] op_sel:[1,0]
	v_mov_b32_e32 v61, v59
	v_pk_add_f32 v[58:59], v[66:67], v[60:61]
	s_nop 0
	v_add_f32_e32 v57, v58, v59
	v_pk_mul_f32 v[50:51], v[56:57], v[64:65] op_sel_hi:[0,1]
	v_pk_mul_f32 v[60:61], v[56:57], v[62:63] op_sel_hi:[0,1]
	v_pk_mul_f32 v[62:63], v[50:51], v[50:51]
	v_pk_mul_f32 v[64:65], v[60:61], v[60:61]
	v_pk_mul_f32 v[52:53], v[56:57], v[52:53] op_sel_hi:[0,1]
	v_pk_mov_b32 v[66:67], v[64:65], v[62:63] op_sel:[1,0]
	v_mov_b32_e32 v65, v63
	v_pk_add_f32 v[62:63], v[66:67], v[64:65]
	v_cvt_pk_bf16_f32 v60, v60, v61
	v_cvt_pk_bf16_f32 v61, v50, v51
	v_pk_mul_f32 v[46:47], v[56:57], v[46:47] op_sel_hi:[0,1]
	v_pk_mul_f32 v[44:45], v[56:57], v[44:45] op_sel_hi:[0,1]
	v_pk_mul_f32 v[50:51], v[56:57], v[54:55] op_sel_hi:[0,1]
	v_mul_f32_e32 v56, v53, v53
	v_pk_add_f32 v[54:55], v[62:63], v[62:63] op_sel:[0,1] op_sel_hi:[1,0]
	v_add_f32_e32 v58, v130, v57
	v_mul_f32_e32 v57, v50, v50
	v_mov_b32_e32 v55, v56
	v_mul_f32_e32 v56, v45, v45
	ds_write2_b64 v134, v[48:49], v[60:61] offset1:4
	v_cvt_pk_bf16_f32 v48, v44, v45
	v_pk_fma_f32 v[44:45], v[44:45], v[44:45], v[56:57] op_sel_hi:[1,1,0]
	v_mul_f32_e32 v56, v47, v47
	v_cvt_pk_bf16_f32 v49, v46, v47
	v_mul_f32_e32 v60, v51, v51
	v_pk_fma_f32 v[46:47], v[46:47], v[46:47], v[56:57] op_sel_hi:[1,1,0]
	v_mul_f32_e32 v59, v52, v52
	v_mov_b32_e32 v45, v57
	v_mov_b32_e32 v47, v60
	v_pk_add_f32 v[54:55], v[58:59], v[54:55]
	v_pk_add_f32 v[44:45], v[44:45], v[46:47]
	s_nop 0
	v_pk_add_f32 v[44:45], v[54:55], v[44:45]
	s_nop 0
	v_add_f32_e32 v130, v44, v45
	v_cvt_pk_bf16_f32 v44, v52, v53
	v_cvt_pk_bf16_f32 v45, v50, v51
	ds_write2_b64 v134, v[48:49], v[44:45] offset0:8 offset1:12
	v_add_u32_e32 v134, 0x80, v134
	s_cbranch_scc0 .LBB0_215
.LBB0_210:
	s_barrier
	global_load_dwordx4 v[44:47], v[122:123], off offset:16
	global_load_dwordx4 v[60:63], v[122:123], off
	global_load_dwordx4 v[52:55], v[122:123], off offset:48
	global_load_dwordx4 v[56:59], v[122:123], off offset:32
	global_load_dwordx4 v[48:51], v[122:123], off offset:80
	global_load_dwordx4 v[72:75], v[122:123], off offset:64
	global_load_dwordx4 v[64:67], v[122:123], off offset:112
	global_load_dwordx4 v[68:71], v[122:123], off offset:96
	s_waitcnt vmcnt(10)
	v_and_b32_e32 v83, 0xffff0000, v8
	v_lshlrev_b32_e32 v84, 16, v8
	v_mul_f32_e32 v96, v83, v83
	v_lshlrev_b32_e32 v82, 16, v9
	v_fmac_f32_e32 v96, v84, v84
	v_and_b32_e32 v81, 0xffff0000, v9
	v_fmac_f32_e32 v96, v82, v82
	v_lshlrev_b32_e32 v80, 16, v10
	v_fmac_f32_e32 v96, v81, v81
	v_and_b32_e32 v98, 0xffff0000, v10
	v_fmac_f32_e32 v96, v80, v80
	v_lshlrev_b32_e32 v99, 16, v11
	v_fmac_f32_e32 v96, v98, v98
	v_and_b32_e32 v100, 0xffff0000, v11
	v_fmac_f32_e32 v96, v99, v99
	v_lshlrev_b32_e32 v101, 16, v16
	v_fmac_f32_e32 v96, v100, v100
	v_and_b32_e32 v102, 0xffff0000, v16
	v_fmac_f32_e32 v96, v101, v101
	v_lshlrev_b32_e32 v103, 16, v17
	v_fmac_f32_e32 v96, v102, v102
	v_and_b32_e32 v104, 0xffff0000, v17
	v_fmac_f32_e32 v96, v103, v103
	v_lshlrev_b32_e32 v105, 16, v18
	v_fmac_f32_e32 v96, v104, v104
	v_and_b32_e32 v106, 0xffff0000, v18
	v_fmac_f32_e32 v96, v105, v105
	v_lshlrev_b32_e32 v107, 16, v19
	v_fmac_f32_e32 v96, v106, v106
	v_and_b32_e32 v108, 0xffff0000, v19
	v_fmac_f32_e32 v96, v107, v107
	v_lshlrev_b32_e32 v109, 16, v12
	v_fmac_f32_e32 v96, v108, v108
	v_and_b32_e32 v94, 0xffff0000, v12
	v_fmac_f32_e32 v96, v109, v109
	v_lshlrev_b32_e32 v92, 16, v13
	v_fmac_f32_e32 v96, v94, v94
	v_and_b32_e32 v95, 0xffff0000, v13
	v_fmac_f32_e32 v96, v92, v92
	v_lshlrev_b32_e32 v93, 16, v14
	v_fmac_f32_e32 v96, v95, v95
	v_and_b32_e32 v91, 0xffff0000, v14
	v_fmac_f32_e32 v96, v93, v93
	v_lshlrev_b32_e32 v90, 16, v15
	v_fmac_f32_e32 v96, v91, v91
	v_and_b32_e32 v89, 0xffff0000, v15
	v_fmac_f32_e32 v96, v90, v90
	v_lshlrev_b32_e32 v88, 16, v4
	v_fmac_f32_e32 v96, v89, v89
	v_and_b32_e32 v87, 0xffff0000, v4
	v_fmac_f32_e32 v96, v88, v88
	v_lshlrev_b32_e32 v86, 16, v5
	v_fmac_f32_e32 v96, v87, v87
	v_and_b32_e32 v85, 0xffff0000, v5
	v_fmac_f32_e32 v96, v86, v86
	v_and_b32_e32 v76, 0xffff0000, v6
	v_lshlrev_b32_e32 v77, 16, v6
	v_fmac_f32_e32 v96, v85, v85
	v_pk_mul_f32 v[78:79], v[76:77], v[76:77]
	s_cmpk_lg_i32 s4, 0x180
	v_add_f32_e32 v79, v79, v96
	v_add_f32_e32 v110, v78, v79
	v_and_b32_e32 v78, 0xffff0000, v7
	v_lshlrev_b32_e32 v79, 16, v7
	v_pk_mul_f32 v[96:97], v[78:79], v[78:79]
	s_cselect_b64 s[2:3], -1, 0
	v_add_f32_e32 v97, v97, v110
	v_add_f32_e32 v96, v96, v97
	s_nop 1
	s_cmpk_eq_i32 s4, 0x180
	s_waitcnt lgkmcnt(0)
	v_add_f32_dpp v96, v96, v96 quad_perm:[1,0,3,2] row_mask:0xf bank_mask:0xf
	v_fmamk_f32 v96, v96, 0x3c800000, v180
	v_rsq_f32_e32 v96, v96
	s_nop 0
	v_mul_f32_e32 v80, v96, v80
	v_mul_f32_e32 v81, v96, v81
	s_waitcnt vmcnt(7)
	v_mul_f32_e32 v80, v44, v80
	v_mul_f32_e32 v44, v96, v98
	v_mul_f32_e32 v82, v96, v82
	s_waitcnt vmcnt(6)
	v_mul_f32_e32 v63, v63, v81
	v_mul_f32_e32 v81, v45, v44
	v_mul_f32_e32 v44, v96, v99
	v_mul_f32_e32 v62, v62, v82
	v_mul_f32_e32 v82, v46, v44
	v_mul_f32_e32 v44, v96, v100
	v_mul_f32_e32 v47, v47, v44
	v_mul_f32_e32 v44, v96, v101
	s_waitcnt vmcnt(4)
	v_mul_f32_e32 v56, v56, v44
	v_mul_f32_e32 v44, v96, v102
	v_mul_f32_e32 v57, v57, v44
	v_mul_f32_e32 v44, v96, v103
	v_mul_f32_e32 v58, v58, v44
	v_mul_f32_e32 v44, v96, v104
	v_mul_f32_e32 v59, v59, v44
	v_mul_f32_e32 v44, v96, v105
	v_mul_f32_e32 v52, v52, v44
	v_mul_f32_e32 v44, v96, v106
	v_mul_f32_e32 v53, v53, v44
	v_mul_f32_e32 v44, v96, v107
	v_mul_f32_e32 v54, v54, v44
	v_mul_f32_e32 v44, v96, v108
	v_mul_f32_e32 v55, v55, v44
	v_mul_f32_e32 v44, v96, v109
	s_waitcnt vmcnt(2)
	v_mul_f32_e32 v72, v72, v44
	v_mul_f32_e32 v44, v96, v94
	v_mul_f32_e32 v73, v73, v44
	v_mul_f32_e32 v44, v96, v92
	v_mul_f32_e32 v74, v74, v44
	v_mul_f32_e32 v44, v96, v95
	v_mul_f32_e32 v75, v75, v44
	v_mul_f32_e32 v44, v96, v93
	v_mul_f32_e32 v48, v48, v44
	v_mul_f32_e32 v44, v96, v91
	v_mul_f32_e32 v49, v49, v44
	v_mul_f32_e32 v44, v96, v90
	v_mul_f32_e32 v50, v50, v44
	v_mul_f32_e32 v44, v96, v89
	v_mul_f32_e32 v51, v51, v44
	v_mul_f32_e32 v44, v96, v88
	s_waitcnt vmcnt(0)
	v_mul_f32_e32 v68, v68, v44
	v_mul_f32_e32 v44, v96, v87
	v_mul_f32_e32 v69, v69, v44
	v_mul_f32_e32 v44, v96, v86
	v_mul_f32_e32 v70, v44, v70
	v_mul_f32_e32 v44, v96, v85
	v_mul_f32_e32 v71, v44, v71
	v_mul_f32_e32 v44, v96, v77
	v_mul_f32_e32 v64, v44, v64
	v_mul_f32_e32 v44, v96, v76
	v_mul_f32_e32 v65, v44, v65
	v_mul_f32_e32 v44, v96, v79
	v_mul_f32_e32 v84, v96, v84
	v_mul_f32_e32 v83, v96, v83
	v_mul_f32_e32 v66, v44, v66
	v_mul_f32_e32 v44, v96, v78
	v_mul_f32_e32 v60, v60, v84
	v_mul_f32_e32 v61, v61, v83
	v_mul_f32_e32 v67, v44, v67
	v_cvt_pk_bf16_f32 v44, v60, v61
	v_cvt_pk_bf16_f32 v45, v62, v63
	v_cvt_pk_bf16_f32 v46, v80, v81
	v_cvt_pk_bf16_f32 v47, v82, v47
	ds_write_b128 v132, v[44:47]
	v_cvt_pk_bf16_f32 v44, v56, v57
	v_cvt_pk_bf16_f32 v45, v58, v59
	v_cvt_pk_bf16_f32 v46, v52, v53
	v_cvt_pk_bf16_f32 v47, v54, v55
	ds_write_b128 v132, v[44:47] offset:16
	v_cvt_pk_bf16_f32 v44, v72, v73
	v_cvt_pk_bf16_f32 v45, v74, v75
	v_cvt_pk_bf16_f32 v46, v48, v49
	v_cvt_pk_bf16_f32 v47, v50, v51
	ds_write_b128 v132, v[44:47] offset:32
	v_cvt_pk_bf16_f32 v44, v68, v69
	v_cvt_pk_bf16_f32 v45, v70, v71
	v_cvt_pk_bf16_f32 v46, v64, v65
	v_cvt_pk_bf16_f32 v47, v66, v67
	ds_write_b128 v132, v[44:47] offset:48
	ds_write_b16 v135, v28 offset:36864
	ds_write_b16_d16_hi v135, v28 offset:37392
	ds_write_b16 v135, v29 offset:37920
	ds_write_b16_d16_hi v135, v29 offset:38448
	ds_write_b16 v135, v30 offset:38976
	ds_write_b16_d16_hi v135, v30 offset:39504
	ds_write_b16 v135, v31 offset:40032
	ds_write_b16_d16_hi v135, v31 offset:40560
	ds_write_b16 v135, v32 offset:41088
	ds_write_b16_d16_hi v135, v32 offset:41616
	ds_write_b16 v135, v33 offset:42144
	ds_write_b16_d16_hi v135, v33 offset:42672
	ds_write_b16 v135, v34 offset:43200
	ds_write_b16_d16_hi v135, v34 offset:43728
	ds_write_b16 v135, v35 offset:44256
	ds_write_b16_d16_hi v135, v35 offset:44784
	ds_write_b16 v135, v36 offset:45312
	ds_write_b16_d16_hi v135, v36 offset:45840
	ds_write_b16 v135, v37 offset:46368
	ds_write_b16_d16_hi v135, v37 offset:46896
	ds_write_b16 v135, v38 offset:47424
	ds_write_b16_d16_hi v135, v38 offset:47952
	ds_write_b16 v135, v39 offset:48480
	ds_write_b16_d16_hi v135, v39 offset:49008
	ds_write_b16 v135, v40 offset:49536
	ds_write_b16_d16_hi v135, v40 offset:50064
	ds_write_b16 v135, v41 offset:50592
	ds_write_b16_d16_hi v135, v41 offset:51120
	ds_write_b16 v135, v42 offset:51648
	ds_write_b16_d16_hi v135, v42 offset:52176
	ds_write_b16 v135, v43 offset:52704
	ds_write_b16_d16_hi v135, v43 offset:53232
	s_waitcnt lgkmcnt(0)
	s_barrier
	s_cbranch_scc1 .LBB0_212
	v_lshl_add_u64 v[4:5], v[126:127], 0, s[4:5]
	s_mov_b64 s[6:7], 0xdbe0080
	v_add_co_u32_e32 v40, vcc, 0xdbe0000, v4
	v_lshl_add_u64 v[16:17], v[4:5], 0, s[6:7]
	s_nop 0
	v_addc_co_u32_e32 v41, vcc, 0, v5, vcc
	global_load_dwordx4 v[8:11], v[40:41], off offset:128
	global_load_dwordx4 v[4:7], v[16:17], off offset:48
	global_load_dwordx4 v[12:15], v[16:17], off offset:32
	s_nop 0
	global_load_dwordx4 v[16:19], v[16:17], off offset:16
	s_nop 0
	global_load_dwordx4 v[28:31], v[40:41], off offset:640
	global_load_dwordx4 v[32:35], v[40:41], off offset:656
	global_load_dwordx4 v[36:39], v[40:41], off offset:672
	s_nop 0
	global_load_dwordx4 v[40:43], v[40:41], off offset:688
	s_mov_b64 s[6:7], s[0:1]
	s_branch .LBB0_213

.LBB0_213:
	v_lshlrev_b32_e32 v72, 16, v24
	v_and_b32_e32 v73, 0xffff0000, v24
	v_lshlrev_b32_e32 v66, 16, v20
	v_and_b32_e32 v67, 0xffff0000, v20
	v_lshlrev_b32_e32 v74, 16, v25
	v_mul_f32_e32 v78, v72, v72
	v_mul_f32_e32 v79, v73, v73
	v_lshlrev_b32_e32 v68, 16, v21
	v_and_b32_e32 v75, 0xffff0000, v25
	v_mul_f32_e32 v80, v74, v74
	v_fmac_f32_e32 v78, v66, v66
	v_fmac_f32_e32 v79, v67, v67
	v_and_b32_e32 v69, 0xffff0000, v21
	v_lshlrev_b32_e32 v76, 16, v26
	v_mul_f32_e32 v81, v75, v75
	v_fmac_f32_e32 v80, v68, v68
	v_add_f32_e32 v78, v78, v79
	v_lshlrev_b32_e32 v70, 16, v22
	v_and_b32_e32 v77, 0xffff0000, v26
	v_mul_f32_e32 v82, v76, v76
	v_fmac_f32_e32 v81, v69, v69
	v_add_f32_e32 v78, v80, v78
	v_and_b32_e32 v71, 0xffff0000, v22
	v_and_b32_e32 v62, 0xffff0000, v27
	v_lshlrev_b32_e32 v63, 16, v27
	v_mul_f32_e32 v83, v77, v77
	v_fmac_f32_e32 v82, v70, v70
	v_add_f32_e32 v78, v81, v78
	v_and_b32_e32 v60, 0xffff0000, v23
	v_lshlrev_b32_e32 v61, 16, v23
	v_pk_mul_f32 v[64:65], v[62:63], v[62:63]
	v_fmac_f32_e32 v83, v71, v71
	v_add_f32_e32 v78, v82, v78
	v_pk_fma_f32 v[64:65], v[60:61], v[60:61], v[64:65]
	v_add_f32_e32 v78, v83, v78
	v_add_f32_e32 v65, v65, v78
	v_add_f32_e32 v64, v64, v65
	v_mov_b32_e32 v65, v64
	s_nop 1
	v_permlane16_swap_b32 v65, v64
	s_andn2_b64 vcc, exec, s[2:3]
	s_waitcnt lgkmcnt(0)
	v_add_f32_e32 v64, v64, v65
	v_mov_b32_e32 v65, v64
	s_nop 1
	v_permlane32_swap_b32 v65, v64
	s_waitcnt lgkmcnt(0)
	v_add_f32_e32 v64, v64, v65
	v_fmamk_f32 v64, v64, 0x3c800000, v180
	v_rsq_f32_e32 v64, v64
	s_nop 0
	v_mul_f32_e32 v64, 0x3e38aa3b, v64
	v_mul_f32_e32 v65, v64, v66
	v_mul_f32_e32 v66, v64, v72
	v_mul_f32_e32 v72, v64, v73
	v_mul_f32_e32 v73, v64, v74
	v_mul_f32_e32 v74, v64, v75
	v_mul_f32_e32 v75, v64, v76
	v_mul_f32_e32 v71, v64, v71
	v_mul_f32_e32 v76, v64, v77
	v_mul_f32_e32 v61, v64, v61
	v_mul_f32_e32 v63, v64, v63
	v_mul_f32_e32 v60, v64, v60
	v_mul_f32_e32 v62, v64, v62
	v_mul_f32_e32 v67, v64, v67
	v_mul_f32_e32 v68, v64, v68
	v_mul_f32_e32 v69, v64, v69
	v_mul_f32_e32 v70, v64, v70
	v_mul_f32_e32 v48, v224, v65
	v_mul_f32_e32 v56, v228, v66
	v_mul_f32_e32 v49, v225, v67
	v_mul_f32_e32 v64, v75, v236
	v_mul_f32_e32 v44, v71, v233
	v_mul_f32_e32 v53, v76, v237
	v_mul_f32_e32 v45, v61, v234
	v_mul_f32_e32 v54, v63, v238
	v_mul_f32_e32 v46, v60, v235
	v_mul_f32_e32 v47, v62, v239
	v_mul_f32_e32 v57, v229, v72
	v_mul_f32_e32 v50, v226, v68
	v_mul_f32_e32 v58, v230, v73
	v_mul_f32_e32 v51, v69, v227
	v_mul_f32_e32 v59, v74, v231
	v_mul_f32_e32 v52, v70, v232
	v_cvt_pk_bf16_f32 v104, v48, v49
	v_cvt_pk_bf16_f32 v105, v50, v51
	v_cvt_pk_bf16_f32 v106, v52, v44
	v_cvt_pk_bf16_f32 v107, v45, v46
	v_cvt_pk_bf16_f32 v44, v56, v57
	v_cvt_pk_bf16_f32 v45, v58, v59
	v_cvt_pk_bf16_f32 v46, v64, v53
	v_cvt_pk_bf16_f32 v47, v54, v47
	s_cbranch_vccnz .LBB0_209
	v_lshl_add_u64 v[24:25], s[6:7], 1, v[120:121]
	global_load_dwordx4 v[20:23], v[24:25], off offset:3584
	s_nop 0
	global_load_dwordx4 v[24:27], v[24:25], off offset:3648
	s_branch .LBB0_209
.LBB0_215:
	s_waitcnt vmcnt(0)
	s_mov_b64 s[0:1], 0x1000
	v_lshl_add_u64 v[16:17], v[118:119], 0, s[0:1]
	v_lshl_add_u64 v[4:5], v[16:17], 0, v[2:3]
	v_mov_b64_e32 v[50:51], v[4:5]
	global_load_dwordx2 v[8:9], v[4:5], off
	v_readlane_b32 s4, v244, 0
	v_readlane_b32 s8, v244, 4
	v_readlane_b32 s9, v244, 5
	v_mov_b32_e32 v14, v130
	s_nop 1
	v_permlane16_swap_b32 v14, v130
	v_readlane_b32 s5, v244, 1
	v_readlane_b32 s6, v244, 2
	v_readlane_b32 s7, v244, 3
	v_readlane_b32 s4, v244, 57
	global_load_dwordx4 v[4:7], v114, s[8:9] offset:3072
	global_load_dwordx2 v[52:53], v[50:51], off offset:32
	global_load_dwordx2 v[54:55], v[50:51], off offset:64
	global_load_dwordx2 v[56:57], v[50:51], off offset:96
	global_load_dwordx4 v[58:61], v114, s[8:9] offset:3136
	global_load_dwordx4 v[62:65], v114, s[8:9] offset:3200
	global_load_dwordx4 v[66:69], v114, s[8:9] offset:3264
	global_load_dwordx2 v[70:71], v[50:51], off offset:128
	global_load_dwordx4 v[72:75], v114, s[8:9] offset:3328
	global_load_dwordx2 v[76:77], v[50:51], off offset:160
	global_load_dwordx2 v[78:79], v[50:51], off offset:192
	global_load_dwordx2 v[80:81], v[50:51], off offset:224
	global_load_dwordx4 v[82:85], v114, s[8:9] offset:3392
	global_load_dwordx4 v[86:89], v114, s[8:9] offset:3456
	global_load_dwordx4 v[90:93], v114, s[8:9] offset:3520
	global_load_dwordx2 v[94:95], v[50:51], off offset:256
	global_load_dwordx4 v[96:99], v114, s[8:9] offset:3584
	global_load_dwordx2 v[100:101], v[50:51], off offset:288
	global_load_dwordx2 v[102:103], v[50:51], off offset:320
	global_load_dwordx2 v[104:105], v[50:51], off offset:352
	global_load_dwordx4 v[106:109], v114, s[8:9] offset:3648
	global_load_dwordx4 v[120:123], v114, s[8:9] offset:3712
	global_load_dwordx4 v[124:127], v114, s[8:9] offset:3776
	global_load_dwordx2 v[110:111], v[50:51], off offset:384
	global_load_dwordx4 v[132:135], v114, s[8:9] offset:3840
	global_load_dwordx2 v[136:137], v[50:51], off offset:416
	global_load_dwordx2 v[138:139], v[50:51], off offset:448
	global_load_dwordx2 v[140:141], v[50:51], off offset:480
	global_load_dwordx4 v[142:145], v114, s[8:9] offset:3904
	global_load_dwordx4 v[146:149], v114, s[8:9] offset:3968
	global_load_dwordx4 v[150:153], v114, s[8:9] offset:4032
	s_waitcnt lgkmcnt(0)
	v_add_f32_e32 v14, v130, v14
	v_mov_b32_e32 v15, v14
	s_nop 1
	v_permlane32_swap_b32 v15, v14
	v_lshlrev_b64 v[10:11], 11, v[116:117]
	v_readlane_b32 s6, v244, 59
	v_readlane_b32 s7, v244, 60
	v_add_u32_e32 v12, s96, v131
	s_mov_b64 s[0:1], 0xdde0600
	v_or_b32_e32 v22, 32, v2
	v_mov_b32_e32 v23, v3
	v_or_b32_e32 v24, 64, v2
	v_mov_b32_e32 v25, v3
	v_or_b32_e32 v18, 0x60, v2
	v_mov_b32_e32 v19, v3
	v_lshl_add_u64 v[10:11], s[6:7], 0, v[10:11]
	s_waitcnt lgkmcnt(0)
	v_add_f32_e32 v14, v14, v15
	v_add3_u32 v26, v12, v115, v2
	v_lshl_add_u64 v[12:13], v[10:11], 0, s[0:1]
	v_lshl_add_u64 v[10:11], v[16:17], 0, v[22:23]
	v_lshl_add_u64 v[20:21], v[16:17], 0, v[24:25]
	v_lshl_add_u64 v[32:33], v[16:17], 0, v[18:19]
	v_fmamk_f32 v14, v14, 0x3b800000, v180
	s_mov_b32 s0, 0x800000
	ds_read2_b64 v[28:31], v26 offset1:4
	s_nop 0
	s_nop 0
	v_mul_f32_e32 v15, 0x4b800000, v14
	v_cmp_gt_f32_e32 vcc, s0, v14
	v_lshl_add_u64 v[34:35], v[12:13], 0, v[2:3]
	s_waitcnt lgkmcnt(0)
	v_lshlrev_b32_e32 v33, 16, v28
	v_cndmask_b32_e32 v14, v14, v15, vcc
	v_rsq_f32_e32 v14, v14
	v_and_b32_e32 v39, 0xffff0000, v28
	v_lshlrev_b32_e32 v41, 16, v29
	v_and_b32_e32 v29, 0xffff0000, v29
	v_mul_f32_e32 v15, 0x45800000, v14
	v_cndmask_b32_e32 v15, v14, v15, vcc
	v_lshl_add_u64 v[18:19], v[12:13], 0, v[18:19]
	v_mov_b32_e32 v44, v15
	v_mov_b32_e32 v46, v15
	v_mov_b32_e32 v48, v15
	v_readlane_b32 s36, v244, 10
	v_readlane_b32 s42, v244, 16
	v_readlane_b32 s43, v244, 17
	v_readlane_b32 s10, v244, 6
	v_readlane_b32 s11, v244, 7
	v_readlane_b32 s5, v244, 58
	s_movk_i32 s0, 0x1000
	v_readlane_b32 s37, v244, 11
	v_readlane_b32 s40, v244, 14
	v_readlane_b32 s41, v244, 15
	s_mov_b32 s3, 0x7f800000
	s_mov_b32 s2, 0x33800000
	v_readlane_b32 s38, v244, 12
	v_readlane_b32 s39, v244, 13
	v_readlane_b32 s44, v244, 18
	v_readlane_b32 s45, v244, 19
	v_readlane_b32 s46, v244, 20
	v_readlane_b32 s47, v244, 21
	v_readlane_b32 s48, v244, 22
	v_readlane_b32 s49, v244, 23
	v_readlane_b32 s50, v244, 24
	v_readlane_b32 s51, v244, 25
	s_waitcnt vmcnt(31)
	v_lshlrev_b32_e32 v32, 16, v8
	v_and_b32_e32 v38, 0xffff0000, v8
	v_mul_f32_e32 v8, 0xbfb8aa3b, v32
	v_exp_f32_e32 v8, v8
	v_lshlrev_b32_e32 v40, 16, v9
	v_and_b32_e32 v28, 0xffff0000, v9
	v_mul_f32_e32 v9, 0xbfb8aa3b, v38
	v_exp_f32_e32 v9, v9
	v_add_f32_e32 v8, 1.0, v8
	v_rcp_f32_e32 v14, v8
	v_mul_f32_e32 v27, 0xbfb8aa3b, v40
	v_exp_f32_e32 v27, v27
	v_add_f32_e32 v43, 1.0, v9
	v_pk_mul_f32 v[8:9], v[14:15], v[32:33]
	v_rcp_f32_e32 v14, v43
	v_mul_f32_e32 v42, 0xbfb8aa3b, v28
	v_exp_f32_e32 v42, v42
	v_add_f32_e32 v27, 1.0, v27
	v_pk_mul_f32 v[32:33], v[14:15], v[38:39]
	v_rcp_f32_e32 v14, v27
	s_waitcnt vmcnt(30)
	v_mul_f32_e32 v4, v4, v9
	v_add_f32_e32 v42, 1.0, v42
	v_mul_f32_e32 v8, v8, v4
	v_mul_f32_e32 v4, v5, v33
	v_mul_f32_e32 v9, v32, v4
	v_pk_mul_f32 v[4:5], v[14:15], v[40:41]
	v_rcp_f32_e32 v14, v42
	v_mul_f32_e32 v5, v6, v5
	v_mul_f32_e32 v6, v4, v5
	v_cvt_pk_bf16_f32 v8, v8, v9
	v_pk_mul_f32 v[4:5], v[14:15], v[28:29]
	s_waitcnt vmcnt(29)
	v_and_b32_e32 v29, 0xffff0000, v52
	v_mul_f32_e32 v5, v7, v5
	v_mul_f32_e32 v4, v4, v5
	v_cvt_pk_bf16_f32 v9, v6, v4
	global_store_dwordx2 v[34:35], v[8:9], off
	v_lshl_add_u64 v[8:9], v[12:13], 0, v[22:23]
	v_lshlrev_b32_e32 v23, 16, v52
	v_lshlrev_b32_e32 v22, 16, v30
	v_and_b32_e32 v28, 0xffff0000, v30
	v_lshlrev_b32_e32 v30, 16, v31
	v_and_b32_e32 v32, 0xffff0000, v31
	v_lshlrev_b32_e32 v31, 16, v53
	v_and_b32_e32 v33, 0xffff0000, v53
	v_mul_f32_e32 v10, 0xbfb8aa3b, v23
	v_mul_f32_e32 v11, 0xbfb8aa3b, v29
	v_mul_f32_e32 v14, 0xbfb8aa3b, v31
	v_mul_f32_e32 v27, 0xbfb8aa3b, v33
	v_exp_f32_e32 v10, v10
	v_exp_f32_e32 v11, v11
	v_exp_f32_e32 v14, v14
	v_exp_f32_e32 v27, v27
	v_add_f32_e32 v10, 1.0, v10
	v_add_f32_e32 v11, 1.0, v11
	v_add_f32_e32 v14, 1.0, v14
	v_add_f32_e32 v27, 1.0, v27
	v_rcp_f32_e32 v35, v10
	v_rcp_f32_e32 v39, v11
	v_rcp_f32_e32 v41, v14
	v_rcp_f32_e32 v43, v27
	v_mov_b32_e32 v34, v15
	v_mov_b32_e32 v38, v15
	v_mov_b32_e32 v40, v15
	v_mov_b32_e32 v42, v15
	v_pk_mul_f32 v[10:11], v[34:35], v[22:23]
	v_pk_mul_f32 v[22:23], v[38:39], v[28:29]
	v_pk_mul_f32 v[28:29], v[40:41], v[30:31]
	v_pk_mul_f32 v[30:31], v[42:43], v[32:33]
	v_mov_b32_e32 v32, v15
	s_waitcnt vmcnt(27)
	v_mul_f32_e32 v4, v58, v10
	v_mul_f32_e32 v5, v59, v22
	v_mul_f32_e32 v6, v60, v28
	v_mul_f32_e32 v7, v61, v30
	v_mul_f32_e32 v4, v4, v11
	v_mul_f32_e32 v5, v5, v23
	v_mul_f32_e32 v6, v6, v29
	v_mul_f32_e32 v7, v7, v31
	v_cvt_pk_bf16_f32 v4, v4, v5
	v_cvt_pk_bf16_f32 v5, v6, v7
	global_store_dwordx2 v[8:9], v[4:5], off
	ds_read2_b64 v[4:7], v26 offset0:8 offset1:12
	v_lshlrev_b32_e32 v29, 16, v55
	v_lshl_add_u64 v[22:23], v[12:13], 0, v[24:25]
	v_lshlrev_b32_e32 v25, 16, v54
	v_and_b32_e32 v31, 0xffff0000, v55
	s_waitcnt lgkmcnt(0)
	v_lshlrev_b32_e32 v28, 16, v5
	v_and_b32_e32 v30, 0xffff0000, v5
	v_and_b32_e32 v5, 0xffff0000, v54
	v_mul_f32_e32 v27, 0xbfb8aa3b, v5
	v_mul_f32_e32 v33, 0xbfb8aa3b, v29
	v_mul_f32_e32 v14, 0xbfb8aa3b, v25
	v_mul_f32_e32 v35, 0xbfb8aa3b, v31
	v_exp_f32_e32 v27, v27
	v_exp_f32_e32 v33, v33
	v_exp_f32_e32 v14, v14
	v_exp_f32_e32 v35, v35
	v_add_f32_e32 v27, 1.0, v27
	v_add_f32_e32 v36, 1.0, v33
	v_add_f32_e32 v14, 1.0, v14
	v_add_f32_e32 v37, 1.0, v35
	v_rcp_f32_e32 v35, v27
	v_rcp_f32_e32 v39, v36
	v_rcp_f32_e32 v33, v14
	v_rcp_f32_e32 v41, v37
	v_lshlrev_b32_e32 v24, 16, v4
	v_and_b32_e32 v4, 0xffff0000, v4
	v_pk_mul_f32 v[4:5], v[34:35], v[4:5]
	v_pk_mul_f32 v[28:29], v[38:39], v[28:29]
	v_pk_mul_f32 v[24:25], v[32:33], v[24:25]
	v_pk_mul_f32 v[30:31], v[40:41], v[30:31]
	v_mov_b32_e32 v36, v15
	s_waitcnt vmcnt(27)
	v_mul_f32_e32 v4, v63, v4
	v_mul_f32_e32 v9, v64, v28
	v_mul_f32_e32 v8, v62, v24
	v_mul_f32_e32 v10, v65, v30
	v_mul_f32_e32 v4, v4, v5
	v_mul_f32_e32 v5, v9, v29
	v_mul_f32_e32 v8, v8, v25
	v_mul_f32_e32 v9, v10, v31
	v_cvt_pk_bf16_f32 v4, v8, v4
	v_cvt_pk_bf16_f32 v5, v5, v9
	global_store_dwordx2 v[22:23], v[4:5], off
	v_or_b32_e32 v10, 0x80, v2
	v_mov_b32_e32 v11, v3
	v_lshl_add_u64 v[4:5], v[16:17], 0, v[10:11]
	v_lshlrev_b32_e32 v28, 16, v7
	v_and_b32_e32 v30, 0xffff0000, v7
	v_lshlrev_b32_e32 v5, 16, v56
	v_and_b32_e32 v7, 0xffff0000, v56
	v_lshlrev_b32_e32 v29, 16, v57
	v_and_b32_e32 v31, 0xffff0000, v57
	v_mul_f32_e32 v14, 0xbfb8aa3b, v5
	v_mul_f32_e32 v20, 0xbfb8aa3b, v7
	v_mul_f32_e32 v21, 0xbfb8aa3b, v29
	v_mul_f32_e32 v27, 0xbfb8aa3b, v31
	v_exp_f32_e32 v14, v14
	v_exp_f32_e32 v20, v20
	v_exp_f32_e32 v21, v21
	v_exp_f32_e32 v27, v27
	v_add_f32_e32 v14, 1.0, v14
	v_add_f32_e32 v20, 1.0, v20
	v_add_f32_e32 v21, 1.0, v21
	v_add_f32_e32 v27, 1.0, v27
	v_rcp_f32_e32 v33, v14
	v_rcp_f32_e32 v35, v20
	v_rcp_f32_e32 v37, v21
	v_rcp_f32_e32 v39, v27
	v_lshlrev_b32_e32 v4, 16, v6
	v_and_b32_e32 v6, 0xffff0000, v6
	v_pk_mul_f32 v[4:5], v[32:33], v[4:5]
	v_pk_mul_f32 v[6:7], v[34:35], v[6:7]
	v_pk_mul_f32 v[20:21], v[36:37], v[28:29]
	v_pk_mul_f32 v[28:29], v[38:39], v[30:31]
	v_lshl_add_u64 v[10:11], v[12:13], 0, v[10:11]
	s_waitcnt vmcnt(27)
	v_mul_f32_e32 v4, v66, v4
	v_mul_f32_e32 v6, v67, v6
	v_mul_f32_e32 v14, v68, v20
	v_mul_f32_e32 v20, v69, v28
	v_mul_f32_e32 v4, v4, v5
	v_mul_f32_e32 v5, v6, v7
	v_mul_f32_e32 v6, v14, v21
	v_mul_f32_e32 v7, v20, v29
	v_cvt_pk_bf16_f32 v4, v4, v5
	v_cvt_pk_bf16_f32 v5, v6, v7
	global_store_dwordx2 v[18:19], v[4:5], off
	ds_read2_b64 v[28:31], v26 offset0:16 offset1:20
	v_or_b32_e32 v22, 0xa0, v2
	v_mov_b32_e32 v23, v3
	v_or_b32_e32 v24, 0xc0, v2
	v_mov_b32_e32 v25, v3
	v_or_b32_e32 v18, 0xe0, v2
	v_mov_b32_e32 v19, v3
	v_lshl_add_u64 v[20:21], v[16:17], 0, v[22:23]
	v_lshl_add_u64 v[32:33], v[16:17], 0, v[24:25]
	v_lshl_add_u64 v[34:35], v[16:17], 0, v[18:19]
	s_nop 0
	s_nop 0
	s_waitcnt lgkmcnt(0)
	v_lshlrev_b32_e32 v38, 16, v29
	v_and_b32_e32 v40, 0xffff0000, v29
	s_waitcnt vmcnt(27)
	v_lshlrev_b32_e32 v35, 16, v70
	v_and_b32_e32 v29, 0xffff0000, v70
	v_lshlrev_b32_e32 v39, 16, v71
	v_and_b32_e32 v41, 0xffff0000, v71
	v_mul_f32_e32 v8, 0xbfb8aa3b, v35
	v_mul_f32_e32 v9, 0xbfb8aa3b, v29
	v_mul_f32_e32 v14, 0xbfb8aa3b, v39
	v_mul_f32_e32 v27, 0xbfb8aa3b, v41
	v_exp_f32_e32 v8, v8
	v_exp_f32_e32 v9, v9
	v_exp_f32_e32 v14, v14
	v_exp_f32_e32 v27, v27
	v_add_f32_e32 v8, 1.0, v8
	v_add_f32_e32 v9, 1.0, v9
	v_add_f32_e32 v14, 1.0, v14
	v_add_f32_e32 v27, 1.0, v27
	v_rcp_f32_e32 v43, v8
	v_rcp_f32_e32 v45, v9
	v_rcp_f32_e32 v47, v14
	v_rcp_f32_e32 v49, v27
	v_lshlrev_b32_e32 v34, 16, v28
	v_and_b32_e32 v28, 0xffff0000, v28
	v_pk_mul_f32 v[8:9], v[42:43], v[34:35]
	v_pk_mul_f32 v[28:29], v[44:45], v[28:29]
	v_pk_mul_f32 v[34:35], v[46:47], v[38:39]
	v_pk_mul_f32 v[38:39], v[48:49], v[40:41]
	v_mov_b32_e32 v40, v15
	v_lshl_add_u64 v[18:19], v[12:13], 0, v[18:19]
	s_waitcnt vmcnt(26)
	v_mul_f32_e32 v4, v72, v8
	v_mul_f32_e32 v5, v73, v28
	v_mul_f32_e32 v6, v74, v34
	v_mul_f32_e32 v7, v75, v38
	v_mul_f32_e32 v4, v4, v9
	v_mul_f32_e32 v5, v5, v29
	v_mul_f32_e32 v6, v6, v35
	v_mul_f32_e32 v7, v7, v39
	v_cvt_pk_bf16_f32 v4, v4, v5
	v_cvt_pk_bf16_f32 v5, v6, v7
	global_store_dwordx2 v[10:11], v[4:5], off
	v_lshl_add_u64 v[8:9], v[12:13], 0, v[22:23]
	s_waitcnt vmcnt(26)
	v_lshlrev_b32_e32 v11, 16, v76
	v_and_b32_e32 v23, 0xffff0000, v76
	v_lshlrev_b32_e32 v10, 16, v30
	v_and_b32_e32 v22, 0xffff0000, v30
	v_lshlrev_b32_e32 v28, 16, v31
	v_and_b32_e32 v30, 0xffff0000, v31
	v_lshlrev_b32_e32 v29, 16, v77
	v_and_b32_e32 v31, 0xffff0000, v77
	v_mul_f32_e32 v14, 0xbfb8aa3b, v11
	v_mul_f32_e32 v27, 0xbfb8aa3b, v23
	v_mul_f32_e32 v35, 0xbfb8aa3b, v29
	v_mul_f32_e32 v36, 0xbfb8aa3b, v31
	v_exp_f32_e32 v14, v14
	v_exp_f32_e32 v27, v27
	v_exp_f32_e32 v35, v35
	v_exp_f32_e32 v36, v36
	v_add_f32_e32 v14, 1.0, v14
	v_add_f32_e32 v27, 1.0, v27
	v_add_f32_e32 v37, 1.0, v35
	v_add_f32_e32 v36, 1.0, v36
	v_rcp_f32_e32 v35, v14
	v_rcp_f32_e32 v39, v27
	v_rcp_f32_e32 v41, v37
	v_rcp_f32_e32 v43, v36
	v_mov_b32_e32 v34, v15
	v_mov_b32_e32 v38, v15
	v_pk_mul_f32 v[10:11], v[34:35], v[10:11]
	v_pk_mul_f32 v[22:23], v[38:39], v[22:23]
	v_pk_mul_f32 v[28:29], v[40:41], v[28:29]
	v_pk_mul_f32 v[30:31], v[42:43], v[30:31]
	v_mov_b32_e32 v36, v15
	s_waitcnt vmcnt(23)
	v_mul_f32_e32 v4, v82, v10
	v_mul_f32_e32 v5, v83, v22
	v_mul_f32_e32 v6, v84, v28
	v_mul_f32_e32 v7, v85, v30
	v_mul_f32_e32 v4, v4, v11
	v_mul_f32_e32 v5, v5, v23
	v_mul_f32_e32 v6, v6, v29
	v_mul_f32_e32 v7, v7, v31
	v_cvt_pk_bf16_f32 v4, v4, v5
	v_cvt_pk_bf16_f32 v5, v6, v7
	global_store_dwordx2 v[8:9], v[4:5], off
	ds_read2_b64 v[4:7], v26 offset0:24 offset1:28
	v_lshlrev_b32_e32 v29, 16, v79
	v_lshl_add_u64 v[22:23], v[12:13], 0, v[24:25]
	v_lshlrev_b32_e32 v25, 16, v78
	v_and_b32_e32 v31, 0xffff0000, v79
	s_waitcnt lgkmcnt(0)
	v_lshlrev_b32_e32 v28, 16, v5
	v_and_b32_e32 v30, 0xffff0000, v5
	v_and_b32_e32 v5, 0xffff0000, v78
	v_mul_f32_e32 v27, 0xbfb8aa3b, v5
	v_mul_f32_e32 v32, 0xbfb8aa3b, v29
	v_mul_f32_e32 v14, 0xbfb8aa3b, v25
	v_mul_f32_e32 v33, 0xbfb8aa3b, v31
	v_exp_f32_e32 v27, v27
	v_exp_f32_e32 v32, v32
	v_exp_f32_e32 v14, v14
	v_exp_f32_e32 v33, v33
	v_add_f32_e32 v27, 1.0, v27
	v_add_f32_e32 v32, 1.0, v32
	v_add_f32_e32 v14, 1.0, v14
	v_add_f32_e32 v33, 1.0, v33
	v_rcp_f32_e32 v37, v27
	v_rcp_f32_e32 v39, v32
	v_rcp_f32_e32 v35, v14
	v_rcp_f32_e32 v41, v33
	v_lshlrev_b32_e32 v24, 16, v4
	v_and_b32_e32 v4, 0xffff0000, v4
	v_pk_mul_f32 v[4:5], v[36:37], v[4:5]
	v_pk_mul_f32 v[28:29], v[38:39], v[28:29]
	v_pk_mul_f32 v[24:25], v[34:35], v[24:25]
	v_pk_mul_f32 v[30:31], v[40:41], v[30:31]
	v_mov_b32_e32 v32, v15
	s_waitcnt vmcnt(23)
	v_mul_f32_e32 v4, v87, v4
	v_mul_f32_e32 v9, v88, v28
	v_mul_f32_e32 v8, v86, v24
	v_mul_f32_e32 v10, v89, v30
	v_mul_f32_e32 v4, v4, v5
	v_mul_f32_e32 v5, v9, v29
	v_mul_f32_e32 v8, v8, v25
	v_mul_f32_e32 v9, v10, v31
	v_cvt_pk_bf16_f32 v4, v8, v4
	v_cvt_pk_bf16_f32 v5, v5, v9
	global_store_dwordx2 v[22:23], v[4:5], off
	v_or_b32_e32 v10, 0x100, v2
	v_mov_b32_e32 v11, v3
	v_lshl_add_u64 v[4:5], v[16:17], 0, v[10:11]
	v_lshlrev_b32_e32 v28, 16, v7
	v_and_b32_e32 v30, 0xffff0000, v7
	v_lshlrev_b32_e32 v5, 16, v80
	v_and_b32_e32 v7, 0xffff0000, v80
	v_lshlrev_b32_e32 v29, 16, v81
	v_and_b32_e32 v31, 0xffff0000, v81
	v_mul_f32_e32 v14, 0xbfb8aa3b, v5
	v_mul_f32_e32 v20, 0xbfb8aa3b, v7
	v_mul_f32_e32 v21, 0xbfb8aa3b, v29
	v_mul_f32_e32 v27, 0xbfb8aa3b, v31
	v_exp_f32_e32 v14, v14
	v_exp_f32_e32 v20, v20
	v_exp_f32_e32 v21, v21
	v_exp_f32_e32 v27, v27
	v_add_f32_e32 v14, 1.0, v14
	v_add_f32_e32 v20, 1.0, v20
	v_add_f32_e32 v21, 1.0, v21
	v_add_f32_e32 v27, 1.0, v27
	v_rcp_f32_e32 v33, v14
	v_rcp_f32_e32 v35, v20
	v_rcp_f32_e32 v37, v21
	v_rcp_f32_e32 v39, v27
	v_lshlrev_b32_e32 v4, 16, v6
	v_and_b32_e32 v6, 0xffff0000, v6
	v_pk_mul_f32 v[4:5], v[32:33], v[4:5]
	v_pk_mul_f32 v[6:7], v[34:35], v[6:7]
	v_pk_mul_f32 v[20:21], v[36:37], v[28:29]
	v_pk_mul_f32 v[28:29], v[38:39], v[30:31]
	v_lshl_add_u64 v[36:37], v[12:13], 0, v[10:11]
	s_waitcnt vmcnt(23)
	v_mul_f32_e32 v4, v90, v4
	v_mul_f32_e32 v6, v91, v6
	v_mul_f32_e32 v14, v92, v20
	v_mul_f32_e32 v20, v93, v28
	v_mul_f32_e32 v4, v4, v5
	v_mul_f32_e32 v5, v6, v7
	v_mul_f32_e32 v6, v14, v21
	v_mul_f32_e32 v7, v20, v29
	v_cvt_pk_bf16_f32 v4, v4, v5
	v_cvt_pk_bf16_f32 v5, v6, v7
	global_store_dwordx2 v[18:19], v[4:5], off
	ds_read2_b64 v[28:31], v26 offset0:32 offset1:36
	v_or_b32_e32 v20, 0x120, v2
	v_mov_b32_e32 v21, v3
	v_or_b32_e32 v22, 0x140, v2
	v_mov_b32_e32 v23, v3
	v_or_b32_e32 v18, 0x160, v2
	v_mov_b32_e32 v19, v3
	v_lshl_add_u64 v[24:25], v[16:17], 0, v[20:21]
	v_lshl_add_u64 v[32:33], v[16:17], 0, v[22:23]
	v_lshl_add_u64 v[34:35], v[16:17], 0, v[18:19]
	s_nop 0
	s_nop 0
	s_waitcnt lgkmcnt(0)
	v_lshlrev_b32_e32 v38, 16, v29
	v_and_b32_e32 v40, 0xffff0000, v29
	s_waitcnt vmcnt(23)
	v_lshlrev_b32_e32 v35, 16, v94
	v_and_b32_e32 v29, 0xffff0000, v94
	v_lshlrev_b32_e32 v39, 16, v95
	v_and_b32_e32 v41, 0xffff0000, v95
	v_mul_f32_e32 v8, 0xbfb8aa3b, v35
	v_mul_f32_e32 v9, 0xbfb8aa3b, v29
	v_mul_f32_e32 v14, 0xbfb8aa3b, v39
	v_mul_f32_e32 v27, 0xbfb8aa3b, v41
	v_exp_f32_e32 v8, v8
	v_exp_f32_e32 v9, v9
	v_exp_f32_e32 v14, v14
	v_exp_f32_e32 v27, v27
	v_add_f32_e32 v8, 1.0, v8
	v_add_f32_e32 v9, 1.0, v9
	v_add_f32_e32 v14, 1.0, v14
	v_add_f32_e32 v27, 1.0, v27
	v_rcp_f32_e32 v43, v8
	v_rcp_f32_e32 v45, v9
	v_rcp_f32_e32 v47, v14
	v_rcp_f32_e32 v49, v27
	v_lshlrev_b32_e32 v34, 16, v28
	v_and_b32_e32 v28, 0xffff0000, v28
	v_pk_mul_f32 v[8:9], v[42:43], v[34:35]
	v_pk_mul_f32 v[28:29], v[44:45], v[28:29]
	v_pk_mul_f32 v[34:35], v[46:47], v[38:39]
	v_pk_mul_f32 v[38:39], v[48:49], v[40:41]
	v_mov_b32_e32 v40, v15
	s_waitcnt vmcnt(22)
	v_mul_f32_e32 v4, v96, v8
	v_mul_f32_e32 v5, v97, v28
	v_mul_f32_e32 v6, v98, v34
	v_mul_f32_e32 v7, v99, v38
	v_mul_f32_e32 v4, v4, v9
	v_mul_f32_e32 v5, v5, v29
	v_mul_f32_e32 v6, v6, v35
	v_mul_f32_e32 v7, v7, v39
	v_cvt_pk_bf16_f32 v4, v4, v5
	v_cvt_pk_bf16_f32 v5, v6, v7
	global_store_dwordx2 v[36:37], v[4:5], off
	v_lshl_add_u64 v[8:9], v[12:13], 0, v[20:21]
	s_waitcnt vmcnt(22)
	v_lshlrev_b32_e32 v21, 16, v100
	v_and_b32_e32 v29, 0xffff0000, v100
	v_lshlrev_b32_e32 v20, 16, v30
	v_and_b32_e32 v28, 0xffff0000, v30
	v_lshlrev_b32_e32 v30, 16, v31
	v_and_b32_e32 v34, 0xffff0000, v31
	v_lshlrev_b32_e32 v31, 16, v101
	v_and_b32_e32 v35, 0xffff0000, v101
	v_mul_f32_e32 v14, 0xbfb8aa3b, v21
	v_mul_f32_e32 v24, 0xbfb8aa3b, v29
	v_mul_f32_e32 v25, 0xbfb8aa3b, v31
	v_mul_f32_e32 v27, 0xbfb8aa3b, v35
	v_exp_f32_e32 v14, v14
	v_exp_f32_e32 v24, v24
	v_exp_f32_e32 v25, v25
	v_exp_f32_e32 v27, v27
	v_add_f32_e32 v14, 1.0, v14
	v_add_f32_e32 v24, 1.0, v24
	v_add_f32_e32 v25, 1.0, v25
	v_add_f32_e32 v27, 1.0, v27
	v_rcp_f32_e32 v37, v14
	v_rcp_f32_e32 v39, v24
	v_rcp_f32_e32 v41, v25
	v_rcp_f32_e32 v43, v27
	v_mov_b32_e32 v36, v15
	v_mov_b32_e32 v38, v15
	v_pk_mul_f32 v[20:21], v[36:37], v[20:21]
	v_pk_mul_f32 v[24:25], v[38:39], v[28:29]
	v_pk_mul_f32 v[28:29], v[40:41], v[30:31]
	v_pk_mul_f32 v[30:31], v[42:43], v[34:35]
	v_mov_b32_e32 v34, v15
	s_waitcnt vmcnt(19)
	v_mul_f32_e32 v4, v106, v20
	v_mul_f32_e32 v5, v107, v24
	v_mul_f32_e32 v6, v108, v28
	v_mul_f32_e32 v7, v109, v30
	v_mul_f32_e32 v4, v4, v21
	v_mul_f32_e32 v5, v5, v25
	v_mul_f32_e32 v6, v6, v29
	v_mul_f32_e32 v7, v7, v31
	v_cvt_pk_bf16_f32 v4, v4, v5
	v_cvt_pk_bf16_f32 v5, v6, v7
	global_store_dwordx2 v[8:9], v[4:5], off
	ds_read2_b64 v[4:7], v26 offset0:40 offset1:44
	v_lshl_add_u64 v[8:9], v[12:13], 0, v[22:23]
	v_lshlrev_b32_e32 v21, 16, v102
	v_lshlrev_b32_e32 v23, 16, v103
	v_and_b32_e32 v25, 0xffff0000, v103
	s_waitcnt lgkmcnt(0)
	v_lshlrev_b32_e32 v22, 16, v5
	v_and_b32_e32 v24, 0xffff0000, v5
	v_and_b32_e32 v5, 0xffff0000, v102
	v_mul_f32_e32 v14, 0xbfb8aa3b, v21
	v_mul_f32_e32 v27, 0xbfb8aa3b, v5
	v_mul_f32_e32 v32, 0xbfb8aa3b, v23
	v_mul_f32_e32 v33, 0xbfb8aa3b, v25
	v_exp_f32_e32 v14, v14
	v_exp_f32_e32 v27, v27
	v_exp_f32_e32 v32, v32
	v_exp_f32_e32 v33, v33
	v_add_f32_e32 v14, 1.0, v14
	v_add_f32_e32 v27, 1.0, v27
	v_add_f32_e32 v32, 1.0, v32
	v_add_f32_e32 v33, 1.0, v33
	v_rcp_f32_e32 v35, v14
	v_rcp_f32_e32 v37, v27
	v_rcp_f32_e32 v39, v32
	v_rcp_f32_e32 v41, v33
	v_lshlrev_b32_e32 v20, 16, v4
	v_and_b32_e32 v4, 0xffff0000, v4
	v_pk_mul_f32 v[20:21], v[34:35], v[20:21]
	v_pk_mul_f32 v[4:5], v[36:37], v[4:5]
	v_pk_mul_f32 v[22:23], v[38:39], v[22:23]
	v_pk_mul_f32 v[24:25], v[40:41], v[24:25]
	v_mov_b32_e32 v32, v15
	s_waitcnt vmcnt(19)
	v_mul_f32_e32 v14, v120, v20
	v_mul_f32_e32 v4, v121, v4
	v_mul_f32_e32 v20, v122, v22
	v_mul_f32_e32 v22, v123, v24
	v_mul_f32_e32 v4, v4, v5
	v_mul_f32_e32 v5, v20, v23
	v_mul_f32_e32 v14, v14, v21
	v_mul_f32_e32 v20, v22, v25
	v_cvt_pk_bf16_f32 v4, v14, v4
	v_cvt_pk_bf16_f32 v5, v5, v20
	global_store_dwordx2 v[8:9], v[4:5], off
	v_or_b32_e32 v20, 0x180, v2
	v_mov_b32_e32 v21, v3
	v_lshl_add_u64 v[4:5], v[16:17], 0, v[20:21]
	v_lshl_add_u64 v[8:9], v[12:13], 0, v[18:19]
	v_lshlrev_b32_e32 v28, 16, v7
	v_and_b32_e32 v30, 0xffff0000, v7
	v_lshlrev_b32_e32 v5, 16, v104
	v_and_b32_e32 v7, 0xffff0000, v104
	v_lshlrev_b32_e32 v29, 16, v105
	v_and_b32_e32 v31, 0xffff0000, v105
	v_mul_f32_e32 v10, 0xbfb8aa3b, v5
	v_mul_f32_e32 v11, 0xbfb8aa3b, v7
	v_mul_f32_e32 v14, 0xbfb8aa3b, v29
	v_mul_f32_e32 v27, 0xbfb8aa3b, v31
	v_exp_f32_e32 v10, v10
	v_exp_f32_e32 v11, v11
	v_exp_f32_e32 v14, v14
	v_exp_f32_e32 v27, v27
	v_add_f32_e32 v10, 1.0, v10
	v_add_f32_e32 v11, 1.0, v11
	v_add_f32_e32 v14, 1.0, v14
	v_add_f32_e32 v27, 1.0, v27
	v_rcp_f32_e32 v33, v10
	v_rcp_f32_e32 v35, v11
	v_rcp_f32_e32 v37, v14
	v_rcp_f32_e32 v39, v27
	v_lshlrev_b32_e32 v4, 16, v6
	v_and_b32_e32 v6, 0xffff0000, v6
	v_pk_mul_f32 v[4:5], v[32:33], v[4:5]
	v_pk_mul_f32 v[6:7], v[34:35], v[6:7]
	v_pk_mul_f32 v[10:11], v[36:37], v[28:29]
	v_pk_mul_f32 v[28:29], v[38:39], v[30:31]
	v_lshl_add_u64 v[20:21], v[12:13], 0, v[20:21]
	s_waitcnt vmcnt(19)
	v_mul_f32_e32 v4, v124, v4
	v_mul_f32_e32 v6, v125, v6
	v_mul_f32_e32 v10, v126, v10
	v_mul_f32_e32 v14, v127, v28
	v_mul_f32_e32 v4, v4, v5
	v_mul_f32_e32 v5, v6, v7
	v_mul_f32_e32 v6, v10, v11
	v_mul_f32_e32 v7, v14, v29
	v_cvt_pk_bf16_f32 v4, v4, v5
	v_cvt_pk_bf16_f32 v5, v6, v7
	global_store_dwordx2 v[8:9], v[4:5], off
	ds_read2_b64 v[8:11], v26 offset0:48 offset1:52
	s_waitcnt vmcnt(19)
	v_lshlrev_b32_e32 v33, 16, v110
	v_lshlrev_b32_e32 v35, 16, v111
	v_and_b32_e32 v37, 0xffff0000, v111
	v_mul_f32_e32 v14, 0xbfb8aa3b, v33
	s_waitcnt lgkmcnt(0)
	v_lshlrev_b32_e32 v34, 16, v9
	v_and_b32_e32 v36, 0xffff0000, v9
	v_and_b32_e32 v9, 0xffff0000, v110
	v_mul_f32_e32 v18, 0xbfb8aa3b, v9
	v_mul_f32_e32 v19, 0xbfb8aa3b, v35
	v_mul_f32_e32 v27, 0xbfb8aa3b, v37
	v_exp_f32_e32 v14, v14
	v_exp_f32_e32 v18, v18
	v_or_b32_e32 v22, 0x1a0, v2
	v_mov_b32_e32 v23, v3
	v_or_b32_e32 v24, 0x1c0, v2
	v_mov_b32_e32 v25, v3
	v_or_b32_e32 v2, 0x1e0, v2
	v_exp_f32_e32 v19, v19
	v_exp_f32_e32 v27, v27
	v_lshl_add_u64 v[28:29], v[16:17], 0, v[22:23]
	v_lshl_add_u64 v[30:31], v[16:17], 0, v[24:25]
	v_lshl_add_u64 v[16:17], v[16:17], 0, v[2:3]
	s_nop 0
	s_nop 0
	v_add_f32_e32 v14, 1.0, v14
	v_add_f32_e32 v18, 1.0, v18
	v_add_f32_e32 v19, 1.0, v19
	v_add_f32_e32 v27, 1.0, v27
	v_rcp_f32_e32 v39, v14
	v_rcp_f32_e32 v41, v18
	v_rcp_f32_e32 v43, v19
	v_rcp_f32_e32 v45, v27
	v_lshlrev_b32_e32 v32, 16, v8
	v_and_b32_e32 v8, 0xffff0000, v8
	v_pk_mul_f32 v[18:19], v[38:39], v[32:33]
	v_pk_mul_f32 v[8:9], v[40:41], v[8:9]
	v_pk_mul_f32 v[32:33], v[42:43], v[34:35]
	v_pk_mul_f32 v[34:35], v[44:45], v[36:37]
	v_mov_b32_e32 v36, v15
	v_mov_b32_e32 v42, v0
	s_waitcnt vmcnt(18)
	v_mul_f32_e32 v4, v132, v18
	v_mul_f32_e32 v5, v133, v8
	v_mul_f32_e32 v6, v134, v32
	v_mul_f32_e32 v7, v135, v34
	v_mul_f32_e32 v4, v4, v19
	v_mul_f32_e32 v5, v5, v9
	v_mul_f32_e32 v6, v6, v33
	v_mul_f32_e32 v7, v7, v35
	v_cvt_pk_bf16_f32 v4, v4, v5
	v_cvt_pk_bf16_f32 v5, v6, v7
	global_store_dwordx2 v[20:21], v[4:5], off
	v_lshl_add_u64 v[8:9], v[12:13], 0, v[22:23]
	v_lshlrev_b32_e32 v20, 16, v11
	v_and_b32_e32 v22, 0xffff0000, v11
	v_lshlrev_b32_e32 v18, 16, v10
	v_and_b32_e32 v10, 0xffff0000, v10
	v_mov_b32_e32 v32, v15
	v_mov_b32_e32 v34, v15
	s_waitcnt vmcnt(18)
	v_lshlrev_b32_e32 v19, 16, v136
	v_and_b32_e32 v11, 0xffff0000, v136
	v_lshlrev_b32_e32 v21, 16, v137
	v_and_b32_e32 v23, 0xffff0000, v137
	v_mul_f32_e32 v14, 0xbfb8aa3b, v19
	v_mul_f32_e32 v27, 0xbfb8aa3b, v11
	v_mul_f32_e32 v28, 0xbfb8aa3b, v21
	v_mul_f32_e32 v29, 0xbfb8aa3b, v23
	v_exp_f32_e32 v14, v14
	v_exp_f32_e32 v27, v27
	v_exp_f32_e32 v28, v28
	v_exp_f32_e32 v29, v29
	v_add_f32_e32 v14, 1.0, v14
	v_add_f32_e32 v27, 1.0, v27
	v_add_f32_e32 v28, 1.0, v28
	v_add_f32_e32 v29, 1.0, v29
	v_rcp_f32_e32 v33, v14
	v_rcp_f32_e32 v35, v27
	v_rcp_f32_e32 v37, v28
	v_rcp_f32_e32 v39, v29
	v_pk_mul_f32 v[18:19], v[32:33], v[18:19]
	v_pk_mul_f32 v[10:11], v[34:35], v[10:11]
	v_pk_mul_f32 v[20:21], v[36:37], v[20:21]
	v_pk_mul_f32 v[22:23], v[38:39], v[22:23]
	v_mov_b32_e32 v28, v15
	s_waitcnt vmcnt(15)
	v_mul_f32_e32 v4, v142, v18
	v_mul_f32_e32 v5, v143, v10
	v_mul_f32_e32 v6, v144, v20
	v_mul_f32_e32 v7, v145, v22
	v_mul_f32_e32 v4, v4, v19
	v_mul_f32_e32 v5, v5, v11
	v_mul_f32_e32 v6, v6, v21
	v_mul_f32_e32 v7, v7, v23
	v_cvt_pk_bf16_f32 v4, v4, v5
	v_cvt_pk_bf16_f32 v5, v6, v7
	global_store_dwordx2 v[8:9], v[4:5], off
	ds_read2_b64 v[4:7], v26 offset0:56 offset1:60
	v_lshl_add_u64 v[18:19], v[12:13], 0, v[24:25]
	v_lshlrev_b32_e32 v23, 16, v139
	v_lshlrev_b32_e32 v21, 16, v138
	v_and_b32_e32 v25, 0xffff0000, v139
	s_waitcnt lgkmcnt(0)
	v_lshlrev_b32_e32 v22, 16, v5
	v_and_b32_e32 v24, 0xffff0000, v5
	v_and_b32_e32 v5, 0xffff0000, v138
	v_mul_f32_e32 v27, 0xbfb8aa3b, v5
	v_mul_f32_e32 v29, 0xbfb8aa3b, v23
	v_mul_f32_e32 v14, 0xbfb8aa3b, v21
	v_mul_f32_e32 v30, 0xbfb8aa3b, v25
	v_exp_f32_e32 v27, v27
	v_exp_f32_e32 v29, v29
	v_exp_f32_e32 v14, v14
	v_exp_f32_e32 v30, v30
	v_add_f32_e32 v31, 1.0, v27
	v_add_f32_e32 v33, 1.0, v29
	v_add_f32_e32 v14, 1.0, v14
	v_add_f32_e32 v30, 1.0, v30
	v_rcp_f32_e32 v29, v31
	v_rcp_f32_e32 v33, v33
	v_rcp_f32_e32 v27, v14
	v_rcp_f32_e32 v35, v30
	v_lshlrev_b32_e32 v20, 16, v4
	v_and_b32_e32 v4, 0xffff0000, v4
	v_mov_b32_e32 v26, v15
	v_pk_mul_f32 v[4:5], v[28:29], v[4:5]
	v_pk_mul_f32 v[22:23], v[32:33], v[22:23]
	v_pk_mul_f32 v[20:21], v[26:27], v[20:21]
	v_pk_mul_f32 v[24:25], v[34:35], v[24:25]
	v_lshlrev_b32_e32 v14, 16, v7
	s_waitcnt vmcnt(15)
	v_mul_f32_e32 v4, v147, v4
	v_mul_f32_e32 v9, v148, v22
	v_mul_f32_e32 v8, v146, v20
	v_mul_f32_e32 v10, v149, v24
	v_mul_f32_e32 v4, v4, v5
	v_mul_f32_e32 v5, v9, v23
	v_mul_f32_e32 v8, v8, v21
	v_mul_f32_e32 v9, v10, v25
	v_cvt_pk_bf16_f32 v4, v8, v4
	v_cvt_pk_bf16_f32 v5, v5, v9
	global_store_dwordx2 v[18:19], v[4:5], off
	v_lshl_add_u64 v[4:5], v[12:13], 0, v[2:3]
	v_and_b32_e32 v18, 0xffff0000, v7
	v_mov_b32_e32 v20, v15
	v_mov_b32_e32 v22, v15
	v_mov_b32_e32 v24, v15
	v_lshlrev_b32_e32 v13, 16, v140
	v_and_b32_e32 v7, 0xffff0000, v140
	v_lshlrev_b32_e32 v15, 16, v141
	v_and_b32_e32 v19, 0xffff0000, v141
	v_mul_f32_e32 v2, 0xbfb8aa3b, v13
	v_mul_f32_e32 v16, 0xbfb8aa3b, v7
	v_mul_f32_e32 v17, 0xbfb8aa3b, v15
	v_mul_f32_e32 v21, 0xbfb8aa3b, v19
	v_exp_f32_e32 v2, v2
	v_exp_f32_e32 v16, v16
	v_exp_f32_e32 v17, v17
	v_exp_f32_e32 v21, v21
	v_add_f32_e32 v2, 1.0, v2
	v_add_f32_e32 v16, 1.0, v16
	v_add_f32_e32 v17, 1.0, v17
	v_add_f32_e32 v27, 1.0, v21
	v_rcp_f32_e32 v21, v2
	v_rcp_f32_e32 v23, v16
	v_rcp_f32_e32 v25, v17
	v_rcp_f32_e32 v27, v27
	v_lshlrev_b32_e32 v12, 16, v6
	v_and_b32_e32 v6, 0xffff0000, v6
	v_pk_mul_f32 v[12:13], v[20:21], v[12:13]
	v_pk_mul_f32 v[6:7], v[22:23], v[6:7]
	v_pk_mul_f32 v[14:15], v[24:25], v[14:15]
	v_pk_mul_f32 v[16:17], v[26:27], v[18:19]
	v_readlane_b32 s4, v244, 32
	v_readlane_b32 s14, v244, 42
	v_readlane_b32 s15, v244, 43
	v_readlane_b32 s16, v244, 44
	v_readlane_b32 s17, v244, 45
	v_readlane_b32 s6, v244, 34
	s_mov_b32 s6, 0xbfb8aa3b
	s_mov_b32 s4, 0x3f2aaaab
	v_readlane_b32 s5, v244, 33
	s_mov_b32 s5, 0x3f317218
	v_readlane_b32 s7, v244, 35
	v_readlane_b32 s8, v244, 36
	v_readlane_b32 s9, v244, 37
	v_readlane_b32 s10, v244, 38
	v_readlane_b32 s11, v244, 39
	v_readlane_b32 s12, v244, 40
	v_readlane_b32 s13, v244, 41
	v_readlane_b32 s18, v244, 46
	v_readlane_b32 s19, v244, 47
	s_waitcnt vmcnt(15)
	v_mul_f32_e32 v2, v150, v12
	v_mul_f32_e32 v6, v151, v6
	v_mul_f32_e32 v8, v152, v14
	v_mul_f32_e32 v9, v153, v16
	v_mul_f32_e32 v6, v6, v7
	v_mul_f32_e32 v7, v8, v15
	v_mul_f32_e32 v2, v2, v13
	v_mul_f32_e32 v8, v9, v17
	v_cvt_pk_bf16_f32 v6, v2, v6
	v_cvt_pk_bf16_f32 v7, v7, v8
	global_store_dwordx2 v[4:5], v[6:7], off
	s_barrier
	s_nop 0
	v_ashrrev_i32_e32 v43, 31, v42
	v_lshlrev_b64 v[4:5], 2, v[42:43]
	v_lshl_add_u64 v[6:7], s[42:43], 0, v[4:5]
	global_load_dword v2, v[6:7], off
	v_lshl_add_u64 v[8:9], s[14:15], 0, v[4:5]
	v_add_co_u32_e32 v6, vcc, s0, v8
	v_bfe_u32 v43, v42, 4, 2
	s_nop 0
	v_addc_co_u32_e32 v7, vcc, 0, v9, vcc
	global_load_dword v14, v[8:9], off
	global_load_dword v15, v[8:9], off offset:2048
	global_load_dword v16, v[6:7], off
	global_load_dword v17, v[6:7], off offset:2048
	v_and_b32_e32 v18, 0xffffffc0, v42
	v_lshl_or_b32 v104, v43, 3, v18
	v_lshl_add_u64 v[18:19], s[16:17], 0, v[4:5]
	v_lshl_add_u64 v[20:21], s[36:37], 0, v[4:5]
	v_lshl_add_u64 v[4:5], s[40:41], 0, v[4:5]
	global_load_dword v18, v[18:19], off
	s_nop 0
	global_load_dword v19, v[20:21], off
	s_nop 0
	global_load_dword v20, v[4:5], off
	v_lshl_add_u32 v30, v42, 5, 0
	v_and_b32_e32 v195, 15, v42
	v_cmp_lt_u32_e32 vcc, 2, v195
	s_or_b64 s[0:1], s[22:23], vcc
	v_mov_b32_e32 v8, v3
	v_mov_b32_e32 v9, v3
	v_mov_b32_e32 v6, v3
	v_mov_b32_e32 v7, v3
	v_mov_b64_e32 v[12:13], v[8:9]
	v_mov_b64_e32 v[10:11], v[6:7]
	v_ashrrev_i32_e32 v105, 31, v104
	s_waitcnt vmcnt(7)
	v_mul_f32_e64 v4, |v2|, s6
	v_exp_f32_e32 v21, v4
	v_max_f32_e64 v2, -v2, -v2
	v_max_f32_e32 v2, 0, v2
	s_waitcnt vmcnt(3)
	ds_write_b128 v30, v[14:17]
	v_add_f32_e32 v14, 1.0, v21
	v_add_f32_e32 v15, -1.0, v14
	v_frexp_mant_f32_e32 v16, v14
	v_cvt_f64_f32_e32 v[4:5], v14
	v_sub_f32_e32 v17, v15, v14
	v_frexp_exp_i32_f64_e32 v4, v[4:5]
	v_cmp_gt_f32_e32 vcc, s4, v16
	v_sub_f32_e32 v15, v21, v15
	v_add_f32_e32 v5, 1.0, v17
	v_subbrev_co_u32_e32 v4, vcc, 0, v4, vcc
	v_add_f32_e32 v5, v15, v5
	v_sub_u32_e32 v15, 0, v4
	v_ldexp_f32 v14, v14, v15
	v_add_f32_e32 v16, -1.0, v14
	v_add_f32_e32 v17, 1.0, v14
	v_ldexp_f32 v5, v5, v15
	v_add_f32_e32 v15, 1.0, v16
	v_add_f32_e32 v22, -1.0, v17
	v_sub_f32_e32 v15, v14, v15
	v_sub_f32_e32 v14, v14, v22
	v_add_f32_e32 v22, v5, v15
	v_add_f32_e32 v5, v5, v14
	v_add_f32_e32 v24, v17, v5
	v_rcp_f32_e32 v25, v24
	v_add_f32_e32 v15, v16, v22
	v_sub_f32_e32 v16, v15, v16
	v_sub_f32_e32 v14, v24, v17
	v_mul_f32_e32 v27, v15, v25
	v_sub_f32_e32 v26, v22, v16
	v_mul_f32_e32 v16, v24, v27
	v_sub_f32_e32 v5, v5, v14
	v_fma_f32 v22, v27, v24, -v16
	v_fmac_f32_e32 v22, v27, v5
	v_add_f32_e32 v14, v16, v22
	v_sub_f32_e32 v17, v15, v14
	v_mov_b32_e32 v23, v14
	v_pk_add_f32 v[14:15], v[14:15], v[16:17] neg_lo:[0,1] neg_hi:[0,1]
	v_cvt_f32_i32_e32 v4, v4
	v_pk_add_f32 v[14:15], v[14:15], v[22:23] neg_lo:[0,1] neg_hi:[0,1]
	v_cmp_neq_f32_e32 vcc, s3, v21
	v_add_f32_e32 v15, v26, v15
	v_add_f32_e32 v14, v14, v15
	v_add_f32_e32 v15, v17, v14
	v_mul_f32_e32 v23, v25, v15
	v_mul_f32_e32 v16, v24, v23
	v_sub_f32_e32 v17, v17, v15
	v_add_f32_e32 v28, v27, v23
	v_fma_f32 v22, v23, v24, -v16
	v_add_f32_e32 v26, v14, v17
	v_sub_f32_e32 v14, v28, v27
	v_fmac_f32_e32 v22, v23, v5
	v_sub_f32_e32 v5, v23, v14
	v_add_f32_e32 v14, v16, v22
	v_sub_f32_e32 v17, v15, v14
	v_mov_b32_e32 v23, v14
	v_pk_add_f32 v[14:15], v[14:15], v[16:17] neg_lo:[0,1] neg_hi:[0,1]
	s_nop 0
	v_pk_add_f32 v[14:15], v[14:15], v[22:23] neg_lo:[0,1] neg_hi:[0,1]
	s_nop 0
	v_add_f32_e32 v15, v26, v15
	v_add_f32_e32 v14, v14, v15
	v_add_f32_e32 v14, v17, v14
	v_mul_f32_e32 v14, v25, v14
	v_add_f32_e32 v5, v5, v14
	v_add_f32_e32 v14, v28, v5
	v_mul_f32_e32 v16, v14, v14
	v_sub_f32_e32 v17, v14, v28
	v_fmamk_f32 v22, v16, 0x3e9b6dac, v181
	v_sub_f32_e32 v17, v5, v17
	v_mul_f32_e32 v5, v14, v16
	v_fmaak_f32 v113, v16, v22, 0x3f2aaada
	v_ldexp_f32 v23, v17, 1
	v_pk_mul_f32 v[16:17], v[4:5], v[112:113]
	v_ldexp_f32 v15, v14, 1
	v_fma_f32 v14, v4, s5, -v16
	v_fmac_f32_e32 v14, 0xb102e308, v4
	v_pk_add_f32 v[4:5], v[16:17], v[14:15]
	v_mov_b32_e32 v22, v16
	v_sub_f32_e32 v26, v5, v15
	v_pk_add_f32 v[24:25], v[4:5], v[16:17] neg_lo:[0,1] neg_hi:[0,1]
	v_sub_f32_e32 v16, v17, v26
	v_add_f32_e32 v23, v23, v16
	v_pk_add_f32 v[16:17], v[4:5], v[22:23]
	v_mov_b32_e32 v15, v4
	v_mov_b32_e32 v25, v17
	v_pk_add_f32 v[28:29], v[14:15], v[24:25] neg_lo:[0,1] neg_hi:[0,1]
	v_pk_add_f32 v[14:15], v[14:15], v[24:25]
	v_mov_b32_e32 v27, v4
	v_pk_add_f32 v[24:25], v[14:15], v[4:5] op_sel:[1,0] op_sel_hi:[0,1] neg_lo:[0,1] neg_hi:[0,1]
	v_mov_b32_e32 v26, v23
	v_mov_b32_e32 v22, v17
	v_mov_b32_e32 v23, v15
	v_pk_mov_b32 v[4:5], v[4:5], v[24:25] op_sel:[1,0]
	v_pk_add_f32 v[16:17], v[16:17], v[24:25] op_sel_hi:[1,0] neg_lo:[0,1] neg_hi:[0,1]
	v_pk_add_f32 v[4:5], v[22:23], v[4:5] neg_lo:[0,1] neg_hi:[0,1]
	v_mov_b32_e32 v16, v28
	v_pk_add_f32 v[4:5], v[26:27], v[4:5] neg_lo:[0,1] neg_hi:[0,1]
	v_mov_b32_e32 v29, v15
	v_pk_add_f32 v[16:17], v[16:17], v[4:5]
	s_nop 0
	v_pk_add_f32 v[22:23], v[16:17], v[16:17] op_sel:[0,1] op_sel_hi:[1,0]
	s_nop 0
	v_pk_add_f32 v[14:15], v[14:15], v[22:23] op_sel:[1,0] op_sel_hi:[0,1]
	v_mov_b32_e32 v17, v14
	v_mov_b32_e32 v5, v22
	v_pk_add_f32 v[22:23], v[16:17], v[28:29] neg_lo:[0,1] neg_hi:[0,1]
	s_nop 0
	v_sub_f32_e32 v15, v16, v22
	v_pk_add_f32 v[4:5], v[4:5], v[22:23] neg_lo:[0,1] neg_hi:[0,1]
	v_sub_f32_e32 v15, v28, v15
	v_add_f32_e32 v4, v4, v15
	v_add_f32_e32 v4, v4, v5
	v_add_f32_e32 v4, v14, v4
	v_cndmask_b32_e32 v4, v185, v4, vcc
	v_cmp_ngt_f32_e32 vcc, -1.0, v21
	v_mov_b64_e32 v[16:17], v[8:9]
	v_mov_b64_e32 v[14:15], v[6:7]
	v_cndmask_b32_e32 v4, v186, v4, vcc
	v_cmp_neq_f32_e32 vcc, -1.0, v21
	s_nop 1
	v_cndmask_b32_e32 v4, v187, v4, vcc
	v_cmp_lt_f32_e64 vcc, |v21|, s2
	s_nop 1
	v_cndmask_b32_e32 v4, v4, v21, vcc
	v_add_f32_e32 v2, v2, v4
	v_mul_f32_e32 v21, 0xc1000000, v2
	s_waitcnt vmcnt(0)
	ds_write_b128 v30, v[18:21] offset:16
	s_and_saveexec_b64 s[2:3], s[0:1]
	s_cbranch_execz .LBB0_217
	v_add3_u32 v2, s20, -3, v195
	v_mov_b64_e32 v[4:5], s[88:89]
	v_mad_i64_i32 v[4:5], s[0:1], v2, s92, v[4:5]
	v_lshl_add_u64 v[4:5], v[104:105], 1, v[4:5]
	global_load_dwordx4 v[14:17], v[4:5], off
	global_load_dwordx4 v[10:13], v[4:5], off offset:64
